# batched loads: GBA side product, EpiResid epilogue base loads hoisted (bf16 and f32 paths), prologue weight transpose
# speedup vs baseline: 1.0001x; 1.0001x over previous
; #define LAS __attribute__((address_space(3)))
; __device__ __forceinline__ void transpose_item(const float* W, int K, int N, bf16_t* WT, int mode, LAS float* scr, int kb, int nb, int lane, const float* kscale, int coff) {
;     const int k0 = 64 * kb, n0 = 32 * nb;
;     const int nn = n0 + (lane & 31) + coff;
; #pragma unroll 8
;     for (int i = 0; i < 32; ++i) { const int kk = 2 * i + (lane >> 5); const float ksc = kscale ? kscale[k0 + kk] : 1.0f; scr[kk * 33 + (lane & 31)] = nn < N ? __builtin_nontemporal_load(W + (size_t)(k0 + kk) * N + nn) * ksc : 0.f; }
; __device__ __forceinline__ void prep_weights(const Ctx& X, LAS unsigned char* lds, int gw, int ngw, int wave, int lane, int it_lo, int it_hi) {
;     LAS float* scr = (LAS float*)(lds + wave * 16384);
;     constexpr int I_IN = (D / 64) * (NINP / 32), I_OUT = (D / 64) * (D / 32), I_G = (D / 64) * (DFF / 32), I_DN = (DFF / 64) * (D / 32);
;     constexpr int PER_L = I_IN + I_OUT + 2 * I_G + I_DN;
;     asm volatile("" : "+v"(lane));
;     for (int it = it_lo + gw; it < it_hi; it += ngw) {
;         const int l = it / PER_L; int r = it % PER_L;
;         if (r < I_IN) { transpose_item(X.in[2] + (size_t)l * D * DIN, D, DIN, WSP(bf16_t, WS_WIN) + (size_t)l * NINP * D, 0, scr, r / (NINP / 32), r % (NINP / 32), lane, X.in[1] + l * D, (r % (NINP / 32)) * 32 >= 2560 ? 8 : 0); continue; } r -= I_IN;
.LBB0_6:
	s_or_b64 exec, exec, s[4:5]
	s_load_dwordx8 s[4:11], s[0:1], 0x80
	s_lshr_b32 s26, s27, 6
	v_and_b32_e32 v232, 63, v224
	s_lshl_b32 s64, s18, 3
	v_mov_b32_e32 v1, v232
	s_waitcnt lgkmcnt(0)
	v_writelane_b32 v252, s4, 16
	s_nop 1
	v_writelane_b32 v252, s5, 17
	v_writelane_b32 v252, s6, 18
	v_writelane_b32 v252, s7, 19
	v_writelane_b32 v252, s8, 20
	v_writelane_b32 v252, s9, 21
	v_writelane_b32 v252, s10, 22
	v_writelane_b32 v252, s11, 23
	s_lshl_b32 s4, s2, 3
	s_add_i32 s4, s26, s4
	s_mov_b32 s52, s4
	s_cmpk_gt_i32 s4, 0x6ff
	s_cbranch_scc1 .LBB0_43
	s_lshl_b32 s20, s26, 14
	s_mov_b32 s22, s52
	v_and_b32_e32 v6, 31, v232
	v_lshrrev_b32_e32 v7, 5, v232
	v_and_b32_e32 v8, 7, v232
	v_lshrrev_b32_e32 v10, 3, v232
	v_lshlrev_b32_e32 v6, 2, v6
	v_lshlrev_b32_e32 v9, 5, v8
	v_mul_u32_u24_e32 v12, 0x420, v8
	v_lshlrev_b32_e32 v8, 4, v8
	v_mul_u32_u24_e32 v11, 0x84, v7
	v_lshl_add_u32 v12, v10, 2, v12
	v_add3_u32 v11, v11, v6, s20
	v_add_u32_e32 v12, s20, v12
	s_cmpk_lt_i32 s22, 1792
	s_cbranch_scc0 .Lprep1_done
.Lprep1_loop:
	s_mov_b32 s4, 0
	s_mov_b32 s5, s22
	s_mul_hi_u32 s20, s5, 0x2492493
	s_mul_i32 s21, s20, 112
	s_sub_u32 s21, s5, s21
	s_lshl_b32 s20, s20, 6
	s_cmpk_ge_u32 s21, 80
	s_cselect_b32 s16, 8, 0
	s_lshl_b32 s21, s21, 5
	s_mul_i32 s100, s20, 3592
	s_add_u32 s100, s100, s21
	s_add_u32 s100, s100, s16
	s_lshl_b32 s100, s100, 2
	s_mul_i32 s101, s4, 0xe08000
	s_add_u32 s100, s100, s101
	v_readlane_b32 s6, v252, 4
	v_readlane_b32 s7, v252, 5
	s_add_u32 s6, s6, s100
	s_addc_u32 s7, s7, 0
	s_movk_i32 s9, 0x3820
	s_lshl_b32 s100, s4, 10
	s_add_u32 s100, s100, s20
	s_lshl_b32 s100, s100, 2
	v_readlane_b32 s10, v252, 2
	v_readlane_b32 s11, v252, 3
	s_add_u32 s10, s10, s100
	s_addc_u32 s11, s11, 0
	s_mov_b32 s16, 1
	s_lshl_b32 s100, s21, 10
	s_add_u32 s100, s100, s20
	s_lshl_b32 s100, s100, 1
	s_mul_i32 s101, s4, 0x700000
	s_add_u32 s100, s100, s101
	s_add_u32 s100, s100, 0x100000
	s_add_u32 s12, s30, s100
	s_addc_u32 s13, s31, 0
	s_movk_i32 s15, 0x800

; __device__ __forceinline__ void transpose_item(const float* W, int K, int N, bf16_t* WT, int mode, LAS float* scr, int kb, int nb, int lane, const float* kscale, int coff) {
;     ...
; #pragma unroll 8
;     for (int i = 0; i < 32; ++i) { const int kk = 2 * i + (lane >> 5); const float ksc = kscale ? kscale[k0 + kk] : 1.0f; scr[kk * 33 + (lane & 31)] = nn < N ? __builtin_nontemporal_load(W + (size_t)(k0 + kk) * N + nn) * ksc : 0.f; }
.Lprep1_ld:
	global_load_dword v24, v13, s[6:7] nt
	s_add_u32 s6, s6, s8
	s_addc_u32 s7, s7, 0
	global_load_dword v25, v13, s[6:7] nt
	s_add_u32 s6, s6, s8
	s_addc_u32 s7, s7, 0
	global_load_dword v26, v13, s[6:7] nt
	s_add_u32 s6, s6, s8
	s_addc_u32 s7, s7, 0
	global_load_dword v27, v13, s[6:7] nt
	s_add_u32 s6, s6, s8
	s_addc_u32 s7, s7, 0
	global_load_dword v28, v13, s[6:7] nt
	s_add_u32 s6, s6, s8
	s_addc_u32 s7, s7, 0
	global_load_dword v29, v13, s[6:7] nt
	s_add_u32 s6, s6, s8
	s_addc_u32 s7, s7, 0
	global_load_dword v30, v13, s[6:7] nt
	s_add_u32 s6, s6, s8
	s_addc_u32 s7, s7, 0
	global_load_dword v31, v13, s[6:7] nt
	s_add_u32 s6, s6, s8
	s_addc_u32 s7, s7, 0
	global_load_dword v32, v13, s[6:7] nt
	s_add_u32 s6, s6, s8
	s_addc_u32 s7, s7, 0
	global_load_dword v33, v13, s[6:7] nt
	s_add_u32 s6, s6, s8
	s_addc_u32 s7, s7, 0
	global_load_dword v34, v13, s[6:7] nt
	s_add_u32 s6, s6, s8
	s_addc_u32 s7, s7, 0
	global_load_dword v35, v13, s[6:7] nt
	s_add_u32 s6, s6, s8
	s_addc_u32 s7, s7, 0
	global_load_dword v36, v13, s[6:7] nt
	s_add_u32 s6, s6, s8
	s_addc_u32 s7, s7, 0
	global_load_dword v37, v13, s[6:7] nt
	s_add_u32 s6, s6, s8
	s_addc_u32 s7, s7, 0
	global_load_dword v38, v13, s[6:7] nt
	s_add_u32 s6, s6, s8
	s_addc_u32 s7, s7, 0
	global_load_dword v39, v13, s[6:7] nt
	s_add_u32 s6, s6, s8
	s_addc_u32 s7, s7, 0
	global_load_dword v40, v13, s[6:7] nt
	s_add_u32 s6, s6, s8
	s_addc_u32 s7, s7, 0
	global_load_dword v41, v13, s[6:7] nt
	s_add_u32 s6, s6, s8
	s_addc_u32 s7, s7, 0
	global_load_dword v42, v13, s[6:7] nt
	s_add_u32 s6, s6, s8
	s_addc_u32 s7, s7, 0
	global_load_dword v43, v13, s[6:7] nt
	s_add_u32 s6, s6, s8
	s_addc_u32 s7, s7, 0
	global_load_dword v44, v13, s[6:7] nt
	s_add_u32 s6, s6, s8
	s_addc_u32 s7, s7, 0
	global_load_dword v45, v13, s[6:7] nt
	s_add_u32 s6, s6, s8
	s_addc_u32 s7, s7, 0
	global_load_dword v46, v13, s[6:7] nt
	s_add_u32 s6, s6, s8
	s_addc_u32 s7, s7, 0
	global_load_dword v47, v13, s[6:7] nt
	s_add_u32 s6, s6, s8
	s_addc_u32 s7, s7, 0
	global_load_dword v48, v13, s[6:7] nt
	s_add_u32 s6, s6, s8
	s_addc_u32 s7, s7, 0
	global_load_dword v49, v13, s[6:7] nt
	s_add_u32 s6, s6, s8
	s_addc_u32 s7, s7, 0
	global_load_dword v50, v13, s[6:7] nt
	s_add_u32 s6, s6, s8
	s_addc_u32 s7, s7, 0
	global_load_dword v51, v13, s[6:7] nt
	s_add_u32 s6, s6, s8
	s_addc_u32 s7, s7, 0
	global_load_dword v52, v13, s[6:7] nt
	s_add_u32 s6, s6, s8
	s_addc_u32 s7, s7, 0
	global_load_dword v53, v13, s[6:7] nt
	s_add_u32 s6, s6, s8
	s_addc_u32 s7, s7, 0
	global_load_dword v54, v13, s[6:7] nt
	s_add_u32 s6, s6, s8
	s_addc_u32 s7, s7, 0
	global_load_dword v55, v13, s[6:7] nt
	s_waitcnt vmcnt(31)
	ds_write_b32 v11, v24
	s_waitcnt vmcnt(30)
	ds_write_b32 v11, v25 offset:264
	s_waitcnt vmcnt(29)
	ds_write_b32 v11, v26 offset:528
	s_waitcnt vmcnt(28)
	ds_write_b32 v11, v27 offset:792
	s_waitcnt vmcnt(27)
	ds_write_b32 v11, v28 offset:1056
	s_waitcnt vmcnt(26)
	ds_write_b32 v11, v29 offset:1320
	s_waitcnt vmcnt(25)
	ds_write_b32 v11, v30 offset:1584
	s_waitcnt vmcnt(24)
	ds_write_b32 v11, v31 offset:1848
	s_waitcnt vmcnt(23)
	ds_write_b32 v11, v32 offset:2112
	s_waitcnt vmcnt(22)
	ds_write_b32 v11, v33 offset:2376
	s_waitcnt vmcnt(21)
	ds_write_b32 v11, v34 offset:2640
	s_waitcnt vmcnt(20)
	ds_write_b32 v11, v35 offset:2904
	s_waitcnt vmcnt(19)
	ds_write_b32 v11, v36 offset:3168
	s_waitcnt vmcnt(18)
	ds_write_b32 v11, v37 offset:3432
	s_waitcnt vmcnt(17)
	ds_write_b32 v11, v38 offset:3696
	s_waitcnt vmcnt(16)
	ds_write_b32 v11, v39 offset:3960
	s_waitcnt vmcnt(15)
	ds_write_b32 v11, v40 offset:4224
	s_waitcnt vmcnt(14)
	ds_write_b32 v11, v41 offset:4488
	s_waitcnt vmcnt(13)
	ds_write_b32 v11, v42 offset:4752
	s_waitcnt vmcnt(12)
	ds_write_b32 v11, v43 offset:5016
	s_waitcnt vmcnt(11)
	ds_write_b32 v11, v44 offset:5280
	s_waitcnt vmcnt(10)
; #define LAS __attribute__((address_space(3)))
; __device__ __forceinline__ unsigned pk2(float lo, float hi) { return pg8::cvt_pk_bf16(lo, hi); }
; __device__ __forceinline__ void transpose_item(const float* W, int K, int N, bf16_t* WT, int mode, LAS float* scr, int kb, int nb, int lane, const float* kscale, int coff) {
;     ...
;     asm volatile("s_waitcnt lgkmcnt(0)" ::: "memory");
;     const int c = lane & 7;
; #pragma unroll
;     for (int j = 0; j < 4; ++j) { const int n = (lane >> 3) + 8 * j; const LAS float* s = scr + (8 * c) * 33 + n;
;         u32x4 o; o.x = pk2(s[0 * 33], s[1 * 33]); o.y = pk2(s[2 * 33], s[3 * 33]); o.z = pk2(s[4 * 33], s[5 * 33]); o.w = pk2(s[6 * 33], s[7 * 33]);
;         const int ng = n0 + n; const int row = mode == 0 ? ng : ((ng >> 7) * 256 + (ng & 127) + (mode == 2 ? 128 : 0));
;         *(u32x4*)(WT + (size_t)row * K + k0 + 8 * c) = o; }
; __device__ __forceinline__ void prep_weights(const Ctx& X, LAS unsigned char* lds, int gw, int ngw, int wave, int lane, int it_lo, int it_hi) {
;     ...
;     for (int it = it_lo + gw; it < it_hi; it += ngw) {
	ds_write_b32 v11, v45 offset:5544
	s_waitcnt vmcnt(9)
	ds_write_b32 v11, v46 offset:5808
	s_waitcnt vmcnt(8)
	ds_write_b32 v11, v47 offset:6072
	s_waitcnt vmcnt(7)
	ds_write_b32 v11, v48 offset:6336
	s_waitcnt vmcnt(6)
	ds_write_b32 v11, v49 offset:6600
	s_waitcnt vmcnt(5)
	ds_write_b32 v11, v50 offset:6864
	s_waitcnt vmcnt(4)
	ds_write_b32 v11, v51 offset:7128
	s_waitcnt vmcnt(3)
	ds_write_b32 v11, v52 offset:7392
	s_waitcnt vmcnt(2)
	ds_write_b32 v11, v53 offset:7656
	s_waitcnt vmcnt(1)
	ds_write_b32 v11, v54 offset:7920
	s_waitcnt vmcnt(0)
	ds_write_b32 v11, v55 offset:8184
	s_waitcnt lgkmcnt(0)
	ds_read2_b32 v[24:25], v12 offset0:0 offset1:33
	ds_read2_b32 v[26:27], v12 offset0:66 offset1:99
	ds_read2_b32 v[28:29], v12 offset0:132 offset1:165
	ds_read2_b32 v[30:31], v12 offset0:198 offset1:231
	ds_read2_b32 v[32:33], v12 offset0:8 offset1:41
	ds_read2_b32 v[34:35], v12 offset0:74 offset1:107
	ds_read2_b32 v[36:37], v12 offset0:140 offset1:173
	ds_read2_b32 v[38:39], v12 offset0:206 offset1:239
	s_waitcnt lgkmcnt(4)
	v_mul_f32_e32 v24, v16, v24
	v_mul_f32_e32 v25, v17, v25
	v_mul_f32_e32 v26, v18, v26
	v_mul_f32_e32 v27, v19, v27
	v_mul_f32_e32 v28, v20, v28
	v_mul_f32_e32 v29, v21, v29
	v_mul_f32_e32 v30, v22, v30
	v_mul_f32_e32 v31, v23, v31
	v_cvt_pk_bf16_f32 v24, v24, v25
	v_cvt_pk_bf16_f32 v25, v26, v27
	v_cvt_pk_bf16_f32 v26, v28, v29
	v_cvt_pk_bf16_f32 v27, v30, v31
	global_store_dwordx4 v14, v[24:27], s[12:13]
	v_add_u32_e32 v14, s14, v14
	s_waitcnt lgkmcnt(0)
	v_mul_f32_e32 v32, v16, v32
	v_mul_f32_e32 v33, v17, v33
	v_mul_f32_e32 v34, v18, v34
	v_mul_f32_e32 v35, v19, v35
	v_mul_f32_e32 v36, v20, v36
	v_mul_f32_e32 v37, v21, v37
	v_mul_f32_e32 v38, v22, v38
	v_mul_f32_e32 v39, v23, v39
	v_cvt_pk_bf16_f32 v32, v32, v33
	v_cvt_pk_bf16_f32 v33, v34, v35
	v_cvt_pk_bf16_f32 v34, v36, v37
	v_cvt_pk_bf16_f32 v35, v38, v39
	global_store_dwordx4 v14, v[32:35], s[12:13]
	v_add_u32_e32 v14, s14, v14
	ds_read2_b32 v[40:41], v12 offset0:16 offset1:49
	ds_read2_b32 v[42:43], v12 offset0:82 offset1:115
	ds_read2_b32 v[44:45], v12 offset0:148 offset1:181
	ds_read2_b32 v[46:47], v12 offset0:214 offset1:247
	ds_read2_b32 v[48:49], v12 offset0:24 offset1:57
	ds_read2_b32 v[50:51], v12 offset0:90 offset1:123
	ds_read2_b32 v[52:53], v12 offset0:156 offset1:189
	ds_read2_b32 v[54:55], v12 offset0:222 offset1:255
	s_waitcnt lgkmcnt(4)
	v_mul_f32_e32 v40, v16, v40
	v_mul_f32_e32 v41, v17, v41
	v_mul_f32_e32 v42, v18, v42
	v_mul_f32_e32 v43, v19, v43
	v_mul_f32_e32 v44, v20, v44
	v_mul_f32_e32 v45, v21, v45
	v_mul_f32_e32 v46, v22, v46
	v_mul_f32_e32 v47, v23, v47
	v_cvt_pk_bf16_f32 v40, v40, v41
	v_cvt_pk_bf16_f32 v41, v42, v43
	v_cvt_pk_bf16_f32 v42, v44, v45
	v_cvt_pk_bf16_f32 v43, v46, v47
	global_store_dwordx4 v14, v[40:43], s[12:13]
	v_add_u32_e32 v14, s14, v14
	s_waitcnt lgkmcnt(0)
	v_mul_f32_e32 v48, v16, v48
	v_mul_f32_e32 v49, v17, v49
	v_mul_f32_e32 v50, v18, v50
	v_mul_f32_e32 v51, v19, v51
	v_mul_f32_e32 v52, v20, v52
	v_mul_f32_e32 v53, v21, v53
	v_mul_f32_e32 v54, v22, v54
	v_mul_f32_e32 v55, v23, v55
	v_cvt_pk_bf16_f32 v48, v48, v49
	v_cvt_pk_bf16_f32 v49, v50, v51
	v_cvt_pk_bf16_f32 v50, v52, v53
	v_cvt_pk_bf16_f32 v51, v54, v55
	global_store_dwordx4 v14, v[48:51], s[12:13]
	s_mul_i32 s20, s18, 8
	s_add_i32 s22, s22, s20
	s_cmpk_lt_i32 s22, 1792
	s_cbranch_scc1 .Lprep1_loop
.Lprep1_done:
.LBB0_43:
	s_lshl_b32 s34, s2, 9
	v_add_u32_e32 v0, s34, v224
	s_mov_b32 s4, 0x8000
	v_cmp_gt_i32_e32 vcc, s4, v0
	s_and_saveexec_b64 s[4:5], vcc
	s_cbranch_execz .LBB0_48
	s_lshl_b32 s6, s18, 9
	v_ashrrev_i32_e32 v1, 31, v0
	v_lshl_add_u64 v[2:3], v[0:1], 1, s[30:31]
	s_mov_b64 s[8:9], 0x1f880000
	s_ashr_i32 s7, s6, 31
	v_lshl_add_u64 v[2:3], v[2:3], 0, s[8:9]
	s_lshl_b64 s[8:9], s[6:7], 1
	s_mov_b64 s[10:11], 0
	s_movk_i32 s7, 0x3820
	v_mov_b32_e32 v5, 0
	s_movk_i32 s14, 0x7fff
	s_branch .LBB0_46

; __global__ void __launch_bounds__(512, 2) fwd_kernel(Ctx X) {
;     ...
;             for (int rb = blockIdx.x; rb < M / 128; rb += G) {
;                 const bf16_t* Ap = XS + (size_t)(rb * 128 + wave * 16 + r) * D + q * 8;
;                 const bf16_t* Bp = WSP(const bf16_t, WS_WBA) + (size_t)l * 16 * D + r * D + q * 8;
;                 f32x4 acc = (f32x4){0.f, 0.f, 0.f, 0.f};
; #pragma unroll 8
;                 for (int ks = 0; ks < 32; ++ks) acc = __builtin_amdgcn_mfma_f32_16x16x32_bf16(*(const bf16x8*)(Ap + ks * 32), *(const bf16x8*)(Bp + ks * 32), acc, 0, 0, 0);
.LBB0_173:
	v_add_co_u32_e32 v200, vcc, 0x1f880000, v12
	s_nop 1
	v_addc_co_u32_e32 v201, vcc, 0, v13, vcc
	global_load_dwordx4 v[22:25], v[18:19], off
	global_load_dwordx4 v[86:89], v[200:201], off
	global_load_dwordx4 v[26:29], v[18:19], off offset:64
	global_load_dwordx4 v[90:93], v[200:201], off offset:64
	global_load_dwordx4 v[30:33], v[18:19], off offset:128
	global_load_dwordx4 v[94:97], v[200:201], off offset:128
	global_load_dwordx4 v[34:37], v[18:19], off offset:192
	global_load_dwordx4 v[98:101], v[200:201], off offset:192
	global_load_dwordx4 v[38:41], v[18:19], off offset:256
	global_load_dwordx4 v[102:105], v[200:201], off offset:256
	global_load_dwordx4 v[42:45], v[18:19], off offset:320
	global_load_dwordx4 v[106:109], v[200:201], off offset:320
	global_load_dwordx4 v[46:49], v[18:19], off offset:384
	global_load_dwordx4 v[114:117], v[200:201], off offset:384
	global_load_dwordx4 v[50:53], v[18:19], off offset:448
	global_load_dwordx4 v[118:121], v[200:201], off offset:448
	global_load_dwordx4 v[54:57], v[18:19], off offset:512
	global_load_dwordx4 v[122:125], v[200:201], off offset:512
	global_load_dwordx4 v[58:61], v[18:19], off offset:576
	global_load_dwordx4 v[126:129], v[200:201], off offset:576
	global_load_dwordx4 v[62:65], v[18:19], off offset:640
	global_load_dwordx4 v[130:133], v[200:201], off offset:640
	global_load_dwordx4 v[66:69], v[18:19], off offset:704
	global_load_dwordx4 v[134:137], v[200:201], off offset:704
	global_load_dwordx4 v[70:73], v[18:19], off offset:768
	global_load_dwordx4 v[138:141], v[200:201], off offset:768
	global_load_dwordx4 v[74:77], v[18:19], off offset:832
	global_load_dwordx4 v[142:145], v[200:201], off offset:832
	global_load_dwordx4 v[78:81], v[18:19], off offset:896
	global_load_dwordx4 v[146:149], v[200:201], off offset:896
	global_load_dwordx4 v[82:85], v[18:19], off offset:960
	global_load_dwordx4 v[150:153], v[200:201], off offset:960
	s_waitcnt vmcnt(30)
	v_mfma_f32_16x16x32_bf16 v[6:9], v[22:25], v[86:89], v[6:9]
	s_waitcnt vmcnt(28)
	v_mfma_f32_16x16x32_bf16 v[6:9], v[26:29], v[90:93], v[6:9]
	s_waitcnt vmcnt(26)
	v_mfma_f32_16x16x32_bf16 v[6:9], v[30:33], v[94:97], v[6:9]
	s_waitcnt vmcnt(24)
	v_mfma_f32_16x16x32_bf16 v[6:9], v[34:37], v[98:101], v[6:9]
	s_waitcnt vmcnt(22)
	v_mfma_f32_16x16x32_bf16 v[6:9], v[38:41], v[102:105], v[6:9]
	s_waitcnt vmcnt(20)
	v_mfma_f32_16x16x32_bf16 v[6:9], v[42:45], v[106:109], v[6:9]
	s_waitcnt vmcnt(18)
	v_mfma_f32_16x16x32_bf16 v[6:9], v[46:49], v[114:117], v[6:9]
	s_waitcnt vmcnt(16)
	v_mfma_f32_16x16x32_bf16 v[6:9], v[50:53], v[118:121], v[6:9]
	s_waitcnt vmcnt(14)
	v_mfma_f32_16x16x32_bf16 v[6:9], v[54:57], v[122:125], v[6:9]
	s_waitcnt vmcnt(12)
	v_mfma_f32_16x16x32_bf16 v[6:9], v[58:61], v[126:129], v[6:9]
	s_waitcnt vmcnt(10)
	v_mfma_f32_16x16x32_bf16 v[6:9], v[62:65], v[130:133], v[6:9]
	s_waitcnt vmcnt(8)
	v_mfma_f32_16x16x32_bf16 v[6:9], v[66:69], v[134:137], v[6:9]
	s_waitcnt vmcnt(6)
	v_mfma_f32_16x16x32_bf16 v[6:9], v[70:73], v[138:141], v[6:9]
	s_waitcnt vmcnt(4)
	v_mfma_f32_16x16x32_bf16 v[6:9], v[74:77], v[142:145], v[6:9]
	s_waitcnt vmcnt(2)
	v_mfma_f32_16x16x32_bf16 v[6:9], v[78:81], v[146:149], v[6:9]
	s_waitcnt vmcnt(0)
	v_mfma_f32_16x16x32_bf16 v[6:9], v[82:85], v[150:153], v[6:9]
	global_load_dwordx4 v[22:25], v[18:19], off offset:1024
	global_load_dwordx4 v[86:89], v[200:201], off offset:1024
	global_load_dwordx4 v[26:29], v[18:19], off offset:1088
	global_load_dwordx4 v[90:93], v[200:201], off offset:1088
	global_load_dwordx4 v[30:33], v[18:19], off offset:1152
	global_load_dwordx4 v[94:97], v[200:201], off offset:1152
	global_load_dwordx4 v[34:37], v[18:19], off offset:1216
	global_load_dwordx4 v[98:101], v[200:201], off offset:1216
	global_load_dwordx4 v[38:41], v[18:19], off offset:1280
	global_load_dwordx4 v[102:105], v[200:201], off offset:1280
	global_load_dwordx4 v[42:45], v[18:19], off offset:1344
	global_load_dwordx4 v[106:109], v[200:201], off offset:1344
	global_load_dwordx4 v[46:49], v[18:19], off offset:1408
	global_load_dwordx4 v[114:117], v[200:201], off offset:1408
	global_load_dwordx4 v[50:53], v[18:19], off offset:1472
	global_load_dwordx4 v[118:121], v[200:201], off offset:1472
	global_load_dwordx4 v[54:57], v[18:19], off offset:1536
	global_load_dwordx4 v[122:125], v[200:201], off offset:1536
	global_load_dwordx4 v[58:61], v[18:19], off offset:1600
	global_load_dwordx4 v[126:129], v[200:201], off offset:1600
	global_load_dwordx4 v[62:65], v[18:19], off offset:1664
	global_load_dwordx4 v[130:133], v[200:201], off offset:1664
	global_load_dwordx4 v[66:69], v[18:19], off offset:1728
	global_load_dwordx4 v[134:137], v[200:201], off offset:1728
	global_load_dwordx4 v[70:73], v[18:19], off offset:1792
	global_load_dwordx4 v[138:141], v[200:201], off offset:1792
	global_load_dwordx4 v[74:77], v[18:19], off offset:1856
	global_load_dwordx4 v[142:145], v[200:201], off offset:1856
	global_load_dwordx4 v[78:81], v[18:19], off offset:1920
	global_load_dwordx4 v[146:149], v[200:201], off offset:1920
	global_load_dwordx4 v[82:85], v[18:19], off offset:1984
	global_load_dwordx4 v[150:153], v[200:201], off offset:1984
	s_waitcnt vmcnt(30)
	v_mfma_f32_16x16x32_bf16 v[6:9], v[22:25], v[86:89], v[6:9]
	s_waitcnt vmcnt(28)
	v_mfma_f32_16x16x32_bf16 v[6:9], v[26:29], v[90:93], v[6:9]
	s_waitcnt vmcnt(26)
	v_mfma_f32_16x16x32_bf16 v[6:9], v[30:33], v[94:97], v[6:9]
	s_waitcnt vmcnt(24)
	v_mfma_f32_16x16x32_bf16 v[6:9], v[34:37], v[98:101], v[6:9]
	s_waitcnt vmcnt(22)
	v_mfma_f32_16x16x32_bf16 v[6:9], v[38:41], v[102:105], v[6:9]
	s_waitcnt vmcnt(20)
	v_mfma_f32_16x16x32_bf16 v[6:9], v[42:45], v[106:109], v[6:9]
	s_waitcnt vmcnt(18)
	v_mfma_f32_16x16x32_bf16 v[6:9], v[46:49], v[114:117], v[6:9]
	s_waitcnt vmcnt(16)
	v_mfma_f32_16x16x32_bf16 v[6:9], v[50:53], v[118:121], v[6:9]
	s_waitcnt vmcnt(14)
	v_mfma_f32_16x16x32_bf16 v[6:9], v[54:57], v[122:125], v[6:9]
	s_waitcnt vmcnt(12)
	v_mfma_f32_16x16x32_bf16 v[6:9], v[58:61], v[126:129], v[6:9]
	s_waitcnt vmcnt(10)
	v_mfma_f32_16x16x32_bf16 v[6:9], v[62:65], v[130:133], v[6:9]
	s_waitcnt vmcnt(8)
	v_mfma_f32_16x16x32_bf16 v[6:9], v[66:69], v[134:137], v[6:9]
	s_waitcnt vmcnt(6)
	v_mfma_f32_16x16x32_bf16 v[6:9], v[70:73], v[138:141], v[6:9]
	s_waitcnt vmcnt(4)
	v_mfma_f32_16x16x32_bf16 v[6:9], v[74:77], v[142:145], v[6:9]
	s_waitcnt vmcnt(2)
	v_mfma_f32_16x16x32_bf16 v[6:9], v[78:81], v[146:149], v[6:9]
	s_waitcnt vmcnt(0)
	v_mfma_f32_16x16x32_bf16 v[6:9], v[82:85], v[150:153], v[6:9]
	s_and_saveexec_b64 s[4:5], s[0:1]
	s_cbranch_execz .LBB0_171
; __global__ void __launch_bounds__(512, 2) fwd_kernel(Ctx X) {
;     ...
;                 if (r < 8) {
; #pragma unroll
;                     for (int j = 0; j < 4; ++j) { const int row = rb * 128 + wave * 16 + 4 * q + j;
;                         WSP(float, WS_GBA)[(size_t)row * 8 + r] = acc[j] * rsqrtf(WSP(const float, WS_RSA)[row] * (1.0f / 1024.0f) + 1e-6f); } }
	s_lshl_b32 s7, s6, 7
	s_add_i32 s7, s7, s63
	v_add_u32_e32 v18, s7, v20
	v_ashrrev_i32_e32 v19, 31, v18
	v_lshl_add_u64 v[22:23], v[18:19], 2, s[72:73]
	global_load_dword v17, v[22:23], off
	v_lshlrev_b64 v[22:23], 5, v[18:19]
	v_lshl_add_u64 v[22:23], v[10:11], 0, v[22:23]
	s_waitcnt vmcnt(0)
	v_fmamk_f32 v17, v17, 0x3a800000, v225
	v_cmp_gt_f32_e32 vcc, s3, v17
	v_mul_f32_e32 v21, 0x4b800000, v17
	s_nop 0
	v_cndmask_b32_e32 v17, v17, v21, vcc
	v_rsq_f32_e32 v17, v17
	s_nop 0
	v_mul_f32_e32 v21, 0x45800000, v17
	v_cndmask_b32_e32 v17, v17, v21, vcc
	v_mul_f32_e32 v6, v6, v17
	global_store_dword v[22:23], v6, off
	v_or_b32_e32 v22, 1, v18
	v_ashrrev_i32_e32 v23, 31, v22
	v_lshl_add_u64 v[24:25], v[22:23], 2, s[72:73]
	global_load_dword v6, v[24:25], off
	s_waitcnt vmcnt(0)
	v_fmamk_f32 v6, v6, 0x3a800000, v225
	v_cmp_gt_f32_e32 vcc, s3, v6
	v_mul_f32_e32 v17, 0x4b800000, v6
	s_nop 0
	v_cndmask_b32_e32 v6, v6, v17, vcc
	v_rsq_f32_e32 v6, v6
	s_nop 0
	v_mul_f32_e32 v17, 0x45800000, v6
	v_cndmask_b32_e32 v6, v6, v17, vcc
	v_mul_f32_e32 v17, v7, v6
	v_lshlrev_b64 v[6:7], 5, v[22:23]
	v_lshl_add_u64 v[6:7], v[10:11], 0, v[6:7]
	global_store_dword v[6:7], v17, off
	v_or_b32_e32 v6, 2, v18
	v_ashrrev_i32_e32 v7, 31, v6
	v_lshl_add_u64 v[22:23], v[6:7], 2, s[72:73]
	global_load_dword v17, v[22:23], off
	v_lshlrev_b64 v[6:7], 5, v[6:7]
	v_lshl_add_u64 v[6:7], v[10:11], 0, v[6:7]
	s_waitcnt vmcnt(0)
	v_fmamk_f32 v17, v17, 0x3a800000, v225
	v_cmp_gt_f32_e32 vcc, s3, v17
	v_mul_f32_e32 v19, 0x4b800000, v17
	s_nop 0
	v_cndmask_b32_e32 v17, v17, v19, vcc
	v_rsq_f32_e32 v17, v17
	s_nop 0
	v_mul_f32_e32 v19, 0x45800000, v17
	v_cndmask_b32_e32 v17, v17, v19, vcc
	v_mul_f32_e32 v8, v8, v17
	global_store_dword v[6:7], v8, off
	v_or_b32_e32 v6, 3, v18
	v_ashrrev_i32_e32 v7, 31, v6
	v_lshl_add_u64 v[18:19], v[6:7], 2, s[72:73]
	global_load_dword v8, v[18:19], off
	v_lshlrev_b64 v[6:7], 5, v[6:7]
	v_lshl_add_u64 v[6:7], v[10:11], 0, v[6:7]
	s_waitcnt vmcnt(0)
	v_fmamk_f32 v8, v8, 0x3a800000, v225
	v_cmp_gt_f32_e32 vcc, s3, v8
	v_mul_f32_e32 v17, 0x4b800000, v8
	s_nop 0
	v_cndmask_b32_e32 v8, v8, v17, vcc
	v_rsq_f32_e32 v8, v8
	s_nop 0
	v_mul_f32_e32 v17, 0x45800000, v8
	v_cndmask_b32_e32 v8, v8, v17, vcc
	v_mul_f32_e32 v8, v9, v8
	global_store_dword v[6:7], v8, off
	s_branch .LBB0_171

;     __device__ __forceinline__ void operator()(const f32x4 (&acc)[2][2][4][2], const Unit& u, int wr, int wc, int fr, int fq, const float (&rsv)[8]) const {
;     ...
;             for (int m = 0; m < 4; ++m) { const size_t off = (size_t)(row0 + ai * HALF + m * 16) * ldc + col0; float sq = 0.f;
; #pragma unroll
;                 for (int bj = 0; bj < 2; ++bj) { const size_t o_ = off + bj * HALF; f32x4 b0, b1;
;                     if (base_b) { const u32x4 w = __builtin_nontemporal_load((const u32x4*)(base_b + o_));
;                         b0 = (f32x4){__uint_as_float(w.x << 16), __uint_as_float(w.x & 0xffff0000u), __uint_as_float(w.y << 16), __uint_as_float(w.y & 0xffff0000u)};
;                         b1 = (f32x4){__uint_as_float(w.z << 16), __uint_as_float(w.z & 0xffff0000u), __uint_as_float(w.w << 16), __uint_as_float(w.w & 0xffff0000u)}; }
;                     else { b0 = __builtin_nontemporal_load((const f32x4*)(base_f + o_)); b1 = __builtin_nontemporal_load((const f32x4*)(base_f + o_ + 4)); }
.LBB0_958:
	v_lshl_add_u32 v164, s92, 8, v155
	v_lshl_or_b32 v162, s36, 8, v173
	v_ashrrev_i32_e32 v165, 31, v164
	v_ashrrev_i32_e32 v163, 31, v162
	v_lshlrev_b64 v[134:135], 10, v[164:165]
	v_lshl_add_u64 v[152:153], v[134:135], 0, v[162:163]
	v_cndmask_b32_e64 v134, 0, 1, s[20:21]
	v_cmp_ne_u32_e64 s[10:11], 1, v134
	s_andn2_b64 vcc, exec, s[20:21]
	v_lshl_add_u64 v[168:169], v[152:153], 1, s[28:29]
	s_cbranch_vccnz .LBB0_1025
	v_mov_b32_e32 v226, v168
	v_mov_b32_e32 v227, v169
	s_mov_b64 s[38:39], 0x8000
	s_mov_b64 s[40:41], 0x28000
	global_load_dwordx4 v[176:179], v[226:227], off nt
	global_load_dwordx4 v[180:183], v[226:227], off offset:256 nt
	v_lshl_add_u64 v[226:227], v[226:227], 0, s[38:39]
	global_load_dwordx4 v[184:187], v[226:227], off nt
	global_load_dwordx4 v[188:191], v[226:227], off offset:256 nt
	v_lshl_add_u64 v[226:227], v[226:227], 0, s[38:39]
	global_load_dwordx4 v[192:195], v[226:227], off nt
	global_load_dwordx4 v[196:199], v[226:227], off offset:256 nt
	v_lshl_add_u64 v[226:227], v[226:227], 0, s[38:39]
	global_load_dwordx4 v[200:203], v[226:227], off nt
	global_load_dwordx4 v[204:207], v[226:227], off offset:256 nt
	v_lshl_add_u64 v[226:227], v[226:227], 0, s[40:41]
	global_load_dwordx4 v[208:211], v[226:227], off nt
	global_load_dwordx4 v[212:215], v[226:227], off offset:256 nt
	v_lshl_add_u64 v[226:227], v[226:227], 0, s[38:39]
	global_load_dwordx4 v[216:219], v[226:227], off nt
	global_load_dwordx4 v[220:223], v[226:227], off offset:256 nt
	v_lshl_add_u64 v[226:227], v[226:227], 0, s[38:39]
	global_load_dwordx4 v[236:239], v[226:227], off nt
	global_load_dwordx4 v[240:243], v[226:227], off offset:256 nt
	v_lshl_add_u64 v[226:227], v[226:227], 0, s[38:39]
	global_load_dwordx4 v[244:247], v[226:227], off nt
	global_load_dwordx4 v[248:251], v[226:227], off offset:256 nt
	s_waitcnt vmcnt(0)
	v_lshlrev_b32_e32 v134, 16, v176
	v_and_b32_e32 v135, 0xffff0000, v176
	v_lshlrev_b32_e32 v136, 16, v177
	v_and_b32_e32 v137, 0xffff0000, v177
	v_lshlrev_b32_e32 v138, 16, v178
	v_and_b32_e32 v139, 0xffff0000, v178
	v_lshlrev_b32_e32 v140, 16, v179
	v_and_b32_e32 v141, 0xffff0000, v179
	v_lshl_add_u64 v[166:167], v[152:153], 2, s[12:13]
	s_cbranch_execnz .LepiA_m0
.LBB0_960:
	v_mov_b32_e32 v226, v166
	v_mov_b32_e32 v227, v167
	s_mov_b64 s[38:39], 0x10000
	global_load_dwordx4 v[176:179], v[226:227], off nt
	global_load_dwordx4 v[180:183], v[226:227], off offset:16 nt
	global_load_dwordx4 v[184:187], v[226:227], off offset:512 nt
	global_load_dwordx4 v[188:191], v[226:227], off offset:528 nt
	v_lshl_add_u64 v[226:227], v[226:227], 0, s[38:39]
	global_load_dwordx4 v[192:195], v[226:227], off nt
	global_load_dwordx4 v[196:199], v[226:227], off offset:16 nt
	global_load_dwordx4 v[200:203], v[226:227], off offset:512 nt
	global_load_dwordx4 v[204:207], v[226:227], off offset:528 nt
	v_lshl_add_u64 v[226:227], v[226:227], 0, s[38:39]
	global_load_dwordx4 v[208:211], v[226:227], off nt
	global_load_dwordx4 v[212:215], v[226:227], off offset:16 nt
	global_load_dwordx4 v[216:219], v[226:227], off offset:512 nt
	global_load_dwordx4 v[220:223], v[226:227], off offset:528 nt
	v_lshl_add_u64 v[226:227], v[226:227], 0, s[38:39]
	global_load_dwordx4 v[236:239], v[226:227], off nt
	global_load_dwordx4 v[240:243], v[226:227], off offset:16 nt
	global_load_dwordx4 v[244:247], v[226:227], off offset:512 nt
	global_load_dwordx4 v[248:251], v[226:227], off offset:528 nt
	s_waitcnt vmcnt(0)
	s_nop 1
	v_mov_b32_e32 v134, v176
	v_mov_b32_e32 v135, v177
	v_mov_b32_e32 v136, v178
	v_mov_b32_e32 v137, v179
	v_mov_b32_e32 v138, v180
	v_mov_b32_e32 v139, v181
	v_mov_b32_e32 v140, v182
	v_mov_b32_e32 v141, v183
	s_branch .LepiA_m0

; __device__ __forceinline__ unsigned cvt_pk_bf16(float lo, float hi) { unsigned r; asm volatile("v_cvt_pk_bf16_f32 %0, %1, %2" : "=v"(r) : "v"(lo), "v"(hi)); return r; }
;     __device__ __forceinline__ void operator()(const f32x4 (&acc)[2][2][4][2], const Unit& u, int wr, int wc, int fr, int fq, const float (&rsv)[8]) const {
;     ...
;                 for (int bj = 0; bj < 2; ++bj) { const size_t o_ = off + bj * HALF; f32x4 b0, b1;
;                     if (base_b) { const u32x4 w = __builtin_nontemporal_load((const u32x4*)(base_b + o_));
;                         b0 = (f32x4){__uint_as_float(w.x << 16), __uint_as_float(w.x & 0xffff0000u), __uint_as_float(w.y << 16), __uint_as_float(w.y & 0xffff0000u)};
;                         b1 = (f32x4){__uint_as_float(w.z << 16), __uint_as_float(w.z & 0xffff0000u), __uint_as_float(w.w << 16), __uint_as_float(w.w & 0xffff0000u)}; }
;                     else { b0 = __builtin_nontemporal_load((const f32x4*)(base_f + o_)); b1 = __builtin_nontemporal_load((const f32x4*)(base_f + o_ + 4)); }
;                     const f32x4 o0 = b0 + acc[ai][bj][m][0], o1 = b1 + acc[ai][bj][m][1];
;                     if (out_f) { *(f32x4*)(out_f + o_) = o0; *(f32x4*)(out_f + o_ + 4) = o1; }
;                     if (out_b) { u32x4 w; w.x = cvt_pk_bf16(o0[0], o0[1]); w.y = cvt_pk_bf16(o0[2], o0[3]); w.z = cvt_pk_bf16(o1[0], o1[1]); w.w = cvt_pk_bf16(o1[2], o1[3]); *(u32x4*)(out_b + o_) = w; }
.LepiA_m0:
	v_pk_add_f32 v[136:137], v[132:133], v[136:137]
	v_pk_add_f32 v[170:171], v[130:131], v[134:135]
	v_pk_add_f32 v[134:135], v[128:129], v[140:141]
	v_pk_add_f32 v[138:139], v[126:127], v[138:139]
	v_lshl_add_u64 v[130:131], v[152:153], 1, s[74:75]
	s_and_b64 vcc, exec, s[10:11]
	v_cvt_pk_bf16_f32 v126, v170, v171
	v_cvt_pk_bf16_f32 v127, v136, v137
	v_cvt_pk_bf16_f32 v128, v138, v139
	v_cvt_pk_bf16_f32 v129, v134, v135
	global_store_dwordx4 v[130:131], v[126:129], off
	s_cbranch_vccnz .LBB0_1026
	s_nop 1
	v_lshlrev_b32_e32 v126, 16, v180
	v_and_b32_e32 v127, 0xffff0000, v180
	v_lshlrev_b32_e32 v128, 16, v181
	v_and_b32_e32 v129, 0xffff0000, v181
	v_lshlrev_b32_e32 v130, 16, v182
	v_and_b32_e32 v131, 0xffff0000, v182
	v_lshlrev_b32_e32 v132, 16, v183
	v_and_b32_e32 v133, 0xffff0000, v183
	s_cbranch_execnz .LepiA_m1
.LBB0_963:
	s_nop 1
	v_mov_b32_e32 v126, v184
	v_mov_b32_e32 v127, v185
	v_mov_b32_e32 v128, v186
	v_mov_b32_e32 v129, v187
	v_mov_b32_e32 v130, v188
	v_mov_b32_e32 v131, v189
	v_mov_b32_e32 v132, v190
	v_mov_b32_e32 v133, v191
	s_branch .LepiA_m1

; __device__ __forceinline__ unsigned cvt_pk_bf16(float lo, float hi) { unsigned r; asm volatile("v_cvt_pk_bf16_f32 %0, %1, %2" : "=v"(r) : "v"(lo), "v"(hi)); return r; }
;     __device__ __forceinline__ void operator()(const f32x4 (&acc)[2][2][4][2], const Unit& u, int wr, int wc, int fr, int fq, const float (&rsv)[8]) const {
;     ...
;                 for (int bj = 0; bj < 2; ++bj) { const size_t o_ = off + bj * HALF; f32x4 b0, b1;
;                     if (base_b) { const u32x4 w = __builtin_nontemporal_load((const u32x4*)(base_b + o_));
;                         b0 = (f32x4){__uint_as_float(w.x << 16), __uint_as_float(w.x & 0xffff0000u), __uint_as_float(w.y << 16), __uint_as_float(w.y & 0xffff0000u)};
;                         b1 = (f32x4){__uint_as_float(w.z << 16), __uint_as_float(w.z & 0xffff0000u), __uint_as_float(w.w << 16), __uint_as_float(w.w & 0xffff0000u)}; }
;                     else { b0 = __builtin_nontemporal_load((const f32x4*)(base_f + o_)); b1 = __builtin_nontemporal_load((const f32x4*)(base_f + o_ + 4)); }
;                     const f32x4 o0 = b0 + acc[ai][bj][m][0], o1 = b1 + acc[ai][bj][m][1];
;                     if (out_f) { *(f32x4*)(out_f + o_) = o0; *(f32x4*)(out_f + o_ + 4) = o1; }
;                     if (out_b) { u32x4 w; w.x = cvt_pk_bf16(o0[0], o0[1]); w.y = cvt_pk_bf16(o0[2], o0[3]); w.z = cvt_pk_bf16(o1[0], o1[1]); w.w = cvt_pk_bf16(o1[2], o1[3]); *(u32x4*)(out_b + o_) = w; }
;                     sq += ((o0[0] * o0[0] + o0[1] * o0[1]) + (o0[2] * o0[2] + o0[3] * o0[3])) + ((o1[0] * o1[0] + o1[1] * o1[1]) + (o1[2] * o1[2] + o1[3] * o1[3])); }
;                 if (rowsq) { sq += __shfl_xor(sq, 16); sq += __shfl_xor(sq, 32); if (fq == 0) atomicAdd(rowsq + row0 + ai * HALF + m * 16, sq); } }
.LepiA_m1:
	v_pk_add_f32 v[124:125], v[124:125], v[128:129]
	v_pk_add_f32 v[122:123], v[122:123], v[126:127]
	v_pk_add_f32 v[126:127], v[120:121], v[132:133]
	v_mul_f32_e32 v120, v123, v123
	v_mul_f32_e32 v121, v124, v124
	v_mul_f32_e32 v136, v136, v136
	v_pk_add_f32 v[118:119], v[118:119], v[130:131]
	v_fmac_f32_e32 v120, v122, v122
	v_fmac_f32_e32 v121, v125, v125
	v_mul_f32_e32 v140, v171, v171
	v_fmac_f32_e32 v136, v137, v137
	v_mul_f32_e32 v137, v138, v138
	v_mul_f32_e32 v134, v134, v134
	v_add_f32_e32 v120, v120, v121
	v_mul_f32_e32 v121, v118, v118
	v_mul_f32_e32 v128, v126, v126
	v_fmac_f32_e32 v140, v170, v170
	v_fmac_f32_e32 v137, v139, v139
	v_fmac_f32_e32 v134, v135, v135
	v_fmac_f32_e32 v121, v119, v119
	v_fmac_f32_e32 v128, v127, v127
	v_add_f32_e32 v136, v140, v136
	v_add_f32_e32 v134, v134, v137
	v_add_f32_e32 v121, v128, v121
	v_add_f32_e32 v136, v136, v134
	v_add_f32_e32 v120, v120, v121
	v_and_b32_e32 v121, 64, v230
	v_add_f32_e32 v128, v136, v120
	v_xor_b32_e32 v120, 16, v230
	v_add_u32_e32 v129, 64, v121
	v_cmp_lt_i32_e32 vcc, v120, v129
	v_lshlrev_b64 v[134:135], 1, v[152:153]
	v_or_b32_e32 v134, 0x100, v134
	v_cndmask_b32_e32 v120, v230, v120, vcc
	v_lshlrev_b32_e32 v136, 2, v120
	ds_bpermute_b32 v130, v136, v128
	v_cvt_pk_bf16_f32 v120, v122, v123
	v_cvt_pk_bf16_f32 v121, v124, v125
	v_cvt_pk_bf16_f32 v122, v118, v119
	v_xor_b32_e32 v119, 32, v230
	v_cmp_lt_i32_e32 vcc, v119, v129
	s_waitcnt lgkmcnt(0)
	v_add_f32_e32 v118, v128, v130
	v_cvt_pk_bf16_f32 v123, v126, v127
	v_lshl_add_u64 v[124:125], s[74:75], 0, v[134:135]
	v_cndmask_b32_e32 v119, v230, v119, vcc
	v_lshlrev_b32_e32 v137, 2, v119
	ds_bpermute_b32 v119, v137, v118
	v_lshl_add_u64 v[126:127], v[164:165], 2, s[52:53]
	global_store_dwordx4 v[124:125], v[120:123], off
	s_and_saveexec_b64 s[4:5], s[6:7]
	s_cbranch_execz .LBB0_966
	s_waitcnt lgkmcnt(0)
	v_add_f32_e32 v118, v118, v119
	global_atomic_add_f32 v[126:127], v118, off
.LBB0_966:
	s_or_b64 exec, exec, s[4:5]
	v_or_b32_e32 v118, 16, v164
	s_waitcnt lgkmcnt(0)
	v_ashrrev_i32_e32 v119, 31, v118
	v_lshlrev_b64 v[118:119], 10, v[118:119]
	v_lshl_add_u64 v[128:129], v[118:119], 0, v[162:163]
	s_and_b64 vcc, exec, s[10:11]
	v_lshl_add_u64 v[132:133], v[128:129], 1, s[28:29]
	s_cbranch_vccnz .LBB0_1027
	s_nop 1
	v_lshlrev_b32_e32 v118, 16, v184
	v_and_b32_e32 v119, 0xffff0000, v184
	v_lshlrev_b32_e32 v120, 16, v185
	v_and_b32_e32 v121, 0xffff0000, v185
	v_lshlrev_b32_e32 v122, 16, v186
	v_and_b32_e32 v123, 0xffff0000, v186
	v_lshlrev_b32_e32 v124, 16, v187
	v_and_b32_e32 v125, 0xffff0000, v187
	v_lshl_add_u64 v[130:131], v[128:129], 2, s[12:13]
	s_cbranch_execnz .LepiA_m2
.LBB0_968:
	s_nop 1
	v_mov_b32_e32 v118, v192
	v_mov_b32_e32 v119, v193
	v_mov_b32_e32 v120, v194
	v_mov_b32_e32 v121, v195
	v_mov_b32_e32 v122, v196
	v_mov_b32_e32 v123, v197
	v_mov_b32_e32 v124, v198
	v_mov_b32_e32 v125, v199
	s_branch .LepiA_m2

; __device__ __forceinline__ unsigned cvt_pk_bf16(float lo, float hi) { unsigned r; asm volatile("v_cvt_pk_bf16_f32 %0, %1, %2" : "=v"(r) : "v"(lo), "v"(hi)); return r; }
;     __device__ __forceinline__ void operator()(const f32x4 (&acc)[2][2][4][2], const Unit& u, int wr, int wc, int fr, int fq, const float (&rsv)[8]) const {
;     ...
;                 for (int bj = 0; bj < 2; ++bj) { const size_t o_ = off + bj * HALF; f32x4 b0, b1;
;                     if (base_b) { const u32x4 w = __builtin_nontemporal_load((const u32x4*)(base_b + o_));
;                         b0 = (f32x4){__uint_as_float(w.x << 16), __uint_as_float(w.x & 0xffff0000u), __uint_as_float(w.y << 16), __uint_as_float(w.y & 0xffff0000u)};
;                         b1 = (f32x4){__uint_as_float(w.z << 16), __uint_as_float(w.z & 0xffff0000u), __uint_as_float(w.w << 16), __uint_as_float(w.w & 0xffff0000u)}; }
;                     else { b0 = __builtin_nontemporal_load((const f32x4*)(base_f + o_)); b1 = __builtin_nontemporal_load((const f32x4*)(base_f + o_ + 4)); }
;                     const f32x4 o0 = b0 + acc[ai][bj][m][0], o1 = b1 + acc[ai][bj][m][1];
;                     if (out_f) { *(f32x4*)(out_f + o_) = o0; *(f32x4*)(out_f + o_ + 4) = o1; }
;                     if (out_b) { u32x4 w; w.x = cvt_pk_bf16(o0[0], o0[1]); w.y = cvt_pk_bf16(o0[2], o0[3]); w.z = cvt_pk_bf16(o1[0], o1[1]); w.w = cvt_pk_bf16(o1[2], o1[3]); *(u32x4*)(out_b + o_) = w; }
.LepiA_m2:
	v_pk_add_f32 v[120:121], v[116:117], v[120:121]
	v_pk_add_f32 v[134:135], v[114:115], v[118:119]
	v_pk_add_f32 v[118:119], v[112:113], v[124:125]
	v_pk_add_f32 v[122:123], v[110:111], v[122:123]
	v_lshl_add_u64 v[114:115], v[128:129], 1, s[74:75]
	s_and_b64 vcc, exec, s[10:11]
	v_cvt_pk_bf16_f32 v110, v134, v135
	v_cvt_pk_bf16_f32 v111, v120, v121
	v_cvt_pk_bf16_f32 v112, v122, v123
	v_cvt_pk_bf16_f32 v113, v118, v119
	global_store_dwordx4 v[114:115], v[110:113], off
	s_cbranch_vccnz .LBB0_1028
	s_nop 1
	v_lshlrev_b32_e32 v110, 16, v188
	v_and_b32_e32 v111, 0xffff0000, v188
	v_lshlrev_b32_e32 v112, 16, v189
	v_and_b32_e32 v113, 0xffff0000, v189
	v_lshlrev_b32_e32 v114, 16, v190
	v_and_b32_e32 v115, 0xffff0000, v190
	v_lshlrev_b32_e32 v116, 16, v191
	v_and_b32_e32 v117, 0xffff0000, v191
	s_cbranch_execnz .LepiA_m3
.LBB0_971:
	s_nop 1
	v_mov_b32_e32 v110, v200
	v_mov_b32_e32 v111, v201
	v_mov_b32_e32 v112, v202
	v_mov_b32_e32 v113, v203
	v_mov_b32_e32 v114, v204
	v_mov_b32_e32 v115, v205
	v_mov_b32_e32 v116, v206
	v_mov_b32_e32 v117, v207
	s_branch .LepiA_m3

; __device__ __forceinline__ unsigned cvt_pk_bf16(float lo, float hi) { unsigned r; asm volatile("v_cvt_pk_bf16_f32 %0, %1, %2" : "=v"(r) : "v"(lo), "v"(hi)); return r; }
;     __device__ __forceinline__ void operator()(const f32x4 (&acc)[2][2][4][2], const Unit& u, int wr, int wc, int fr, int fq, const float (&rsv)[8]) const {
;     ...
;                 for (int bj = 0; bj < 2; ++bj) { const size_t o_ = off + bj * HALF; f32x4 b0, b1;
;                     if (base_b) { const u32x4 w = __builtin_nontemporal_load((const u32x4*)(base_b + o_));
;                         b0 = (f32x4){__uint_as_float(w.x << 16), __uint_as_float(w.x & 0xffff0000u), __uint_as_float(w.y << 16), __uint_as_float(w.y & 0xffff0000u)};
;                         b1 = (f32x4){__uint_as_float(w.z << 16), __uint_as_float(w.z & 0xffff0000u), __uint_as_float(w.w << 16), __uint_as_float(w.w & 0xffff0000u)}; }
;                     else { b0 = __builtin_nontemporal_load((const f32x4*)(base_f + o_)); b1 = __builtin_nontemporal_load((const f32x4*)(base_f + o_ + 4)); }
;                     const f32x4 o0 = b0 + acc[ai][bj][m][0], o1 = b1 + acc[ai][bj][m][1];
;                     if (out_f) { *(f32x4*)(out_f + o_) = o0; *(f32x4*)(out_f + o_ + 4) = o1; }
;                     if (out_b) { u32x4 w; w.x = cvt_pk_bf16(o0[0], o0[1]); w.y = cvt_pk_bf16(o0[2], o0[3]); w.z = cvt_pk_bf16(o1[0], o1[1]); w.w = cvt_pk_bf16(o1[2], o1[3]); *(u32x4*)(out_b + o_) = w; }
;                     sq += ((o0[0] * o0[0] + o0[1] * o0[1]) + (o0[2] * o0[2] + o0[3] * o0[3])) + ((o1[0] * o1[0] + o1[1] * o1[1]) + (o1[2] * o1[2] + o1[3] * o1[3])); }
;                 if (rowsq) { sq += __shfl_xor(sq, 16); sq += __shfl_xor(sq, 32); if (fq == 0) atomicAdd(rowsq + row0 + ai * HALF + m * 16, sq); } }
.LepiA_m3:
	v_pk_add_f32 v[108:109], v[108:109], v[112:113]
	v_pk_add_f32 v[106:107], v[106:107], v[110:111]
	v_pk_add_f32 v[110:111], v[104:105], v[116:117]
	v_mul_f32_e32 v104, v107, v107
	v_mul_f32_e32 v105, v108, v108
	v_mul_f32_e32 v120, v120, v120
	v_pk_add_f32 v[102:103], v[102:103], v[114:115]
	v_fmac_f32_e32 v104, v106, v106
	v_fmac_f32_e32 v105, v109, v109
	v_mul_f32_e32 v124, v135, v135
	v_fmac_f32_e32 v120, v121, v121
	v_mul_f32_e32 v121, v122, v122
	v_mul_f32_e32 v118, v118, v118
	v_add_f32_e32 v104, v104, v105
	v_mul_f32_e32 v105, v102, v102
	v_mul_f32_e32 v112, v110, v110
	v_fmac_f32_e32 v124, v134, v134
	v_fmac_f32_e32 v121, v123, v123
	v_fmac_f32_e32 v118, v119, v119
	v_fmac_f32_e32 v105, v103, v103
	v_fmac_f32_e32 v112, v111, v111
	v_add_f32_e32 v120, v124, v120
	v_add_f32_e32 v118, v118, v121
	v_add_f32_e32 v105, v112, v105
	v_add_f32_e32 v118, v120, v118
	v_add_f32_e32 v104, v104, v105
	v_add_f32_e32 v114, v118, v104
	ds_bpermute_b32 v115, v136, v114
	v_cvt_pk_bf16_f32 v104, v106, v107
	v_cvt_pk_bf16_f32 v105, v108, v109
	v_cvt_pk_bf16_f32 v106, v102, v103
	v_lshlrev_b64 v[112:113], 1, v[128:129]
	s_waitcnt lgkmcnt(0)
	v_add_f32_e32 v102, v114, v115
	ds_bpermute_b32 v103, v137, v102
	v_or_b32_e32 v112, 0x100, v112
	v_lshl_add_u64 v[108:109], s[74:75], 0, v[112:113]
	v_cvt_pk_bf16_f32 v107, v110, v111
	global_store_dwordx4 v[108:109], v[104:107], off
	s_and_saveexec_b64 s[4:5], s[6:7]
	s_cbranch_execz .LBB0_974
	s_waitcnt lgkmcnt(0)
	v_add_f32_e32 v102, v102, v103
	global_atomic_add_f32 v[126:127], v102, off offset:64
.LBB0_974:
	s_or_b64 exec, exec, s[4:5]
	v_or_b32_e32 v102, 32, v164
	s_waitcnt lgkmcnt(0)
	v_ashrrev_i32_e32 v103, 31, v102
	v_lshlrev_b64 v[102:103], 10, v[102:103]
	v_lshl_add_u64 v[110:111], v[102:103], 0, v[162:163]
	s_and_b64 vcc, exec, s[10:11]
	v_lshl_add_u64 v[114:115], v[110:111], 1, s[28:29]
	s_cbranch_vccnz .LBB0_1029
	s_nop 1
	v_lshlrev_b32_e32 v102, 16, v192
	v_and_b32_e32 v103, 0xffff0000, v192
	v_lshlrev_b32_e32 v104, 16, v193
	v_and_b32_e32 v105, 0xffff0000, v193
	v_lshlrev_b32_e32 v106, 16, v194
	v_and_b32_e32 v107, 0xffff0000, v194
	v_lshlrev_b32_e32 v108, 16, v195
	v_and_b32_e32 v109, 0xffff0000, v195
	v_lshl_add_u64 v[112:113], v[110:111], 2, s[12:13]
	s_cbranch_execnz .LepiA_m4
.LBB0_976:
	s_nop 1
	v_mov_b32_e32 v102, v208
	v_mov_b32_e32 v103, v209
	v_mov_b32_e32 v104, v210
	v_mov_b32_e32 v105, v211
	v_mov_b32_e32 v106, v212
	v_mov_b32_e32 v107, v213
	v_mov_b32_e32 v108, v214
	v_mov_b32_e32 v109, v215
	s_branch .LepiA_m4

; __device__ __forceinline__ unsigned cvt_pk_bf16(float lo, float hi) { unsigned r; asm volatile("v_cvt_pk_bf16_f32 %0, %1, %2" : "=v"(r) : "v"(lo), "v"(hi)); return r; }
;     __device__ __forceinline__ void operator()(const f32x4 (&acc)[2][2][4][2], const Unit& u, int wr, int wc, int fr, int fq, const float (&rsv)[8]) const {
;     ...
;                 for (int bj = 0; bj < 2; ++bj) { const size_t o_ = off + bj * HALF; f32x4 b0, b1;
;                     if (base_b) { const u32x4 w = __builtin_nontemporal_load((const u32x4*)(base_b + o_));
;                         b0 = (f32x4){__uint_as_float(w.x << 16), __uint_as_float(w.x & 0xffff0000u), __uint_as_float(w.y << 16), __uint_as_float(w.y & 0xffff0000u)};
;                         b1 = (f32x4){__uint_as_float(w.z << 16), __uint_as_float(w.z & 0xffff0000u), __uint_as_float(w.w << 16), __uint_as_float(w.w & 0xffff0000u)}; }
;                     else { b0 = __builtin_nontemporal_load((const f32x4*)(base_f + o_)); b1 = __builtin_nontemporal_load((const f32x4*)(base_f + o_ + 4)); }
;                     const f32x4 o0 = b0 + acc[ai][bj][m][0], o1 = b1 + acc[ai][bj][m][1];
;                     if (out_f) { *(f32x4*)(out_f + o_) = o0; *(f32x4*)(out_f + o_ + 4) = o1; }
;                     if (out_b) { u32x4 w; w.x = cvt_pk_bf16(o0[0], o0[1]); w.y = cvt_pk_bf16(o0[2], o0[3]); w.z = cvt_pk_bf16(o1[0], o1[1]); w.w = cvt_pk_bf16(o1[2], o1[3]); *(u32x4*)(out_b + o_) = w; }
.LepiA_m4:
	v_pk_add_f32 v[104:105], v[100:101], v[104:105]
	v_pk_add_f32 v[116:117], v[98:99], v[102:103]
	v_pk_add_f32 v[102:103], v[96:97], v[108:109]
	v_pk_add_f32 v[106:107], v[94:95], v[106:107]
	v_lshl_add_u64 v[98:99], v[110:111], 1, s[74:75]
	s_and_b64 vcc, exec, s[10:11]
	v_cvt_pk_bf16_f32 v94, v116, v117
	v_cvt_pk_bf16_f32 v95, v104, v105
	v_cvt_pk_bf16_f32 v96, v106, v107
	v_cvt_pk_bf16_f32 v97, v102, v103
	global_store_dwordx4 v[98:99], v[94:97], off
	s_cbranch_vccnz .LBB0_1030
	s_nop 1
	v_lshlrev_b32_e32 v94, 16, v196
	v_and_b32_e32 v95, 0xffff0000, v196
	v_lshlrev_b32_e32 v96, 16, v197
	v_and_b32_e32 v97, 0xffff0000, v197
	v_lshlrev_b32_e32 v98, 16, v198
	v_and_b32_e32 v99, 0xffff0000, v198
	v_lshlrev_b32_e32 v100, 16, v199
	v_and_b32_e32 v101, 0xffff0000, v199
	s_cbranch_execnz .LepiA_m5
.LBB0_979:
	s_nop 1
	v_mov_b32_e32 v94, v216
	v_mov_b32_e32 v95, v217
	v_mov_b32_e32 v96, v218
	v_mov_b32_e32 v97, v219
	v_mov_b32_e32 v98, v220
	v_mov_b32_e32 v99, v221
	v_mov_b32_e32 v100, v222
	v_mov_b32_e32 v101, v223
	s_branch .LepiA_m5

; __device__ __forceinline__ unsigned cvt_pk_bf16(float lo, float hi) { unsigned r; asm volatile("v_cvt_pk_bf16_f32 %0, %1, %2" : "=v"(r) : "v"(lo), "v"(hi)); return r; }
;     __device__ __forceinline__ void operator()(const f32x4 (&acc)[2][2][4][2], const Unit& u, int wr, int wc, int fr, int fq, const float (&rsv)[8]) const {
;     ...
;                 for (int bj = 0; bj < 2; ++bj) { const size_t o_ = off + bj * HALF; f32x4 b0, b1;
;                     if (base_b) { const u32x4 w = __builtin_nontemporal_load((const u32x4*)(base_b + o_));
;                         b0 = (f32x4){__uint_as_float(w.x << 16), __uint_as_float(w.x & 0xffff0000u), __uint_as_float(w.y << 16), __uint_as_float(w.y & 0xffff0000u)};
;                         b1 = (f32x4){__uint_as_float(w.z << 16), __uint_as_float(w.z & 0xffff0000u), __uint_as_float(w.w << 16), __uint_as_float(w.w & 0xffff0000u)}; }
;                     else { b0 = __builtin_nontemporal_load((const f32x4*)(base_f + o_)); b1 = __builtin_nontemporal_load((const f32x4*)(base_f + o_ + 4)); }
;                     const f32x4 o0 = b0 + acc[ai][bj][m][0], o1 = b1 + acc[ai][bj][m][1];
;                     if (out_f) { *(f32x4*)(out_f + o_) = o0; *(f32x4*)(out_f + o_ + 4) = o1; }
;                     if (out_b) { u32x4 w; w.x = cvt_pk_bf16(o0[0], o0[1]); w.y = cvt_pk_bf16(o0[2], o0[3]); w.z = cvt_pk_bf16(o1[0], o1[1]); w.w = cvt_pk_bf16(o1[2], o1[3]); *(u32x4*)(out_b + o_) = w; }
;                     sq += ((o0[0] * o0[0] + o0[1] * o0[1]) + (o0[2] * o0[2] + o0[3] * o0[3])) + ((o1[0] * o1[0] + o1[1] * o1[1]) + (o1[2] * o1[2] + o1[3] * o1[3])); }
;                 if (rowsq) { sq += __shfl_xor(sq, 16); sq += __shfl_xor(sq, 32); if (fq == 0) atomicAdd(rowsq + row0 + ai * HALF + m * 16, sq); } }
.LepiA_m5:
	v_pk_add_f32 v[92:93], v[92:93], v[96:97]
	v_pk_add_f32 v[90:91], v[90:91], v[94:95]
	v_pk_add_f32 v[94:95], v[88:89], v[100:101]
	v_mul_f32_e32 v88, v91, v91
	v_mul_f32_e32 v89, v92, v92
	v_mul_f32_e32 v104, v104, v104
	v_pk_add_f32 v[86:87], v[86:87], v[98:99]
	v_fmac_f32_e32 v88, v90, v90
	v_fmac_f32_e32 v89, v93, v93
	v_mul_f32_e32 v108, v117, v117
	v_fmac_f32_e32 v104, v105, v105
	v_mul_f32_e32 v105, v106, v106
	v_mul_f32_e32 v102, v102, v102
	v_add_f32_e32 v88, v88, v89
	v_mul_f32_e32 v89, v86, v86
	v_mul_f32_e32 v96, v94, v94
	v_fmac_f32_e32 v108, v116, v116
	v_fmac_f32_e32 v105, v107, v107
	v_fmac_f32_e32 v102, v103, v103
	v_fmac_f32_e32 v89, v87, v87
	v_fmac_f32_e32 v96, v95, v95
	v_add_f32_e32 v104, v108, v104
	v_add_f32_e32 v102, v102, v105
	v_add_f32_e32 v89, v96, v89
	v_add_f32_e32 v102, v104, v102
	v_add_f32_e32 v88, v88, v89
	v_add_f32_e32 v98, v102, v88
	ds_bpermute_b32 v99, v136, v98
	v_cvt_pk_bf16_f32 v88, v90, v91
	v_cvt_pk_bf16_f32 v89, v92, v93
	v_cvt_pk_bf16_f32 v90, v86, v87
	v_lshlrev_b64 v[96:97], 1, v[110:111]
	s_waitcnt lgkmcnt(0)
	v_add_f32_e32 v86, v98, v99
	ds_bpermute_b32 v87, v137, v86
	v_or_b32_e32 v96, 0x100, v96
	v_lshl_add_u64 v[92:93], s[74:75], 0, v[96:97]
	v_cvt_pk_bf16_f32 v91, v94, v95
	global_store_dwordx4 v[92:93], v[88:91], off
	s_and_saveexec_b64 s[4:5], s[6:7]
	s_cbranch_execz .LBB0_982
	s_waitcnt lgkmcnt(0)
	v_add_f32_e32 v86, v86, v87
	global_atomic_add_f32 v[126:127], v86, off offset:128
.LBB0_982:
	s_or_b64 exec, exec, s[4:5]
	v_or_b32_e32 v86, 48, v164
	s_waitcnt lgkmcnt(0)
	v_ashrrev_i32_e32 v87, 31, v86
	v_lshlrev_b64 v[86:87], 10, v[86:87]
	v_lshl_add_u64 v[94:95], v[86:87], 0, v[162:163]
	s_and_b64 vcc, exec, s[10:11]
	v_lshl_add_u64 v[98:99], v[94:95], 1, s[28:29]
	s_cbranch_vccnz .LBB0_1031
	s_nop 1
	v_lshlrev_b32_e32 v86, 16, v200
	v_and_b32_e32 v87, 0xffff0000, v200
	v_lshlrev_b32_e32 v88, 16, v201
	v_and_b32_e32 v89, 0xffff0000, v201
	v_lshlrev_b32_e32 v90, 16, v202
	v_and_b32_e32 v91, 0xffff0000, v202
	v_lshlrev_b32_e32 v92, 16, v203
	v_and_b32_e32 v93, 0xffff0000, v203
	v_lshl_add_u64 v[96:97], v[94:95], 2, s[12:13]
	s_cbranch_execnz .LepiA_m6
.LBB0_984:
	s_nop 1
	v_mov_b32_e32 v86, v236
	v_mov_b32_e32 v87, v237
	v_mov_b32_e32 v88, v238
	v_mov_b32_e32 v89, v239
	v_mov_b32_e32 v90, v240
	v_mov_b32_e32 v91, v241
	v_mov_b32_e32 v92, v242
	v_mov_b32_e32 v93, v243
	s_branch .LepiA_m6

; __device__ __forceinline__ unsigned cvt_pk_bf16(float lo, float hi) { unsigned r; asm volatile("v_cvt_pk_bf16_f32 %0, %1, %2" : "=v"(r) : "v"(lo), "v"(hi)); return r; }
;     __device__ __forceinline__ void operator()(const f32x4 (&acc)[2][2][4][2], const Unit& u, int wr, int wc, int fr, int fq, const float (&rsv)[8]) const {
;     ...
;                 for (int bj = 0; bj < 2; ++bj) { const size_t o_ = off + bj * HALF; f32x4 b0, b1;
;                     if (base_b) { const u32x4 w = __builtin_nontemporal_load((const u32x4*)(base_b + o_));
;                         b0 = (f32x4){__uint_as_float(w.x << 16), __uint_as_float(w.x & 0xffff0000u), __uint_as_float(w.y << 16), __uint_as_float(w.y & 0xffff0000u)};
;                         b1 = (f32x4){__uint_as_float(w.z << 16), __uint_as_float(w.z & 0xffff0000u), __uint_as_float(w.w << 16), __uint_as_float(w.w & 0xffff0000u)}; }
;                     else { b0 = __builtin_nontemporal_load((const f32x4*)(base_f + o_)); b1 = __builtin_nontemporal_load((const f32x4*)(base_f + o_ + 4)); }
;                     const f32x4 o0 = b0 + acc[ai][bj][m][0], o1 = b1 + acc[ai][bj][m][1];
;                     if (out_f) { *(f32x4*)(out_f + o_) = o0; *(f32x4*)(out_f + o_ + 4) = o1; }
;                     if (out_b) { u32x4 w; w.x = cvt_pk_bf16(o0[0], o0[1]); w.y = cvt_pk_bf16(o0[2], o0[3]); w.z = cvt_pk_bf16(o1[0], o1[1]); w.w = cvt_pk_bf16(o1[2], o1[3]); *(u32x4*)(out_b + o_) = w; }
.LepiA_m6:
	v_pk_add_f32 v[88:89], v[84:85], v[88:89]
	v_pk_add_f32 v[100:101], v[82:83], v[86:87]
	v_pk_add_f32 v[86:87], v[80:81], v[92:93]
	v_pk_add_f32 v[90:91], v[78:79], v[90:91]
	v_lshl_add_u64 v[82:83], v[94:95], 1, s[74:75]
	s_and_b64 vcc, exec, s[10:11]
	v_cvt_pk_bf16_f32 v78, v100, v101
	v_cvt_pk_bf16_f32 v79, v88, v89
	v_cvt_pk_bf16_f32 v80, v90, v91
	v_cvt_pk_bf16_f32 v81, v86, v87
	global_store_dwordx4 v[82:83], v[78:81], off
	s_cbranch_vccnz .LBB0_1032
	s_nop 1
	v_lshlrev_b32_e32 v78, 16, v204
	v_and_b32_e32 v79, 0xffff0000, v204
	v_lshlrev_b32_e32 v80, 16, v205
	v_and_b32_e32 v81, 0xffff0000, v205
	v_lshlrev_b32_e32 v82, 16, v206
	v_and_b32_e32 v83, 0xffff0000, v206
	v_lshlrev_b32_e32 v84, 16, v207
	v_and_b32_e32 v85, 0xffff0000, v207
	s_cbranch_execnz .LepiA_m7
.LBB0_987:
	s_nop 1
	v_mov_b32_e32 v78, v244
	v_mov_b32_e32 v79, v245
	v_mov_b32_e32 v80, v246
	v_mov_b32_e32 v81, v247
	v_mov_b32_e32 v82, v248
	v_mov_b32_e32 v83, v249
	v_mov_b32_e32 v84, v250
	v_mov_b32_e32 v85, v251
	s_branch .LepiA_m7

; __device__ __forceinline__ unsigned cvt_pk_bf16(float lo, float hi) { unsigned r; asm volatile("v_cvt_pk_bf16_f32 %0, %1, %2" : "=v"(r) : "v"(lo), "v"(hi)); return r; }
;     __device__ __forceinline__ void operator()(const f32x4 (&acc)[2][2][4][2], const Unit& u, int wr, int wc, int fr, int fq, const float (&rsv)[8]) const {
;     ...
;             for (int m = 0; m < 4; ++m) { const size_t off = (size_t)(row0 + ai * HALF + m * 16) * ldc + col0; float sq = 0.f;
; #pragma unroll
;                 for (int bj = 0; bj < 2; ++bj) { const size_t o_ = off + bj * HALF; f32x4 b0, b1;
;                     if (base_b) { const u32x4 w = __builtin_nontemporal_load((const u32x4*)(base_b + o_));
;                         b0 = (f32x4){__uint_as_float(w.x << 16), __uint_as_float(w.x & 0xffff0000u), __uint_as_float(w.y << 16), __uint_as_float(w.y & 0xffff0000u)};
;                         b1 = (f32x4){__uint_as_float(w.z << 16), __uint_as_float(w.z & 0xffff0000u), __uint_as_float(w.w << 16), __uint_as_float(w.w & 0xffff0000u)}; }
;                     else { b0 = __builtin_nontemporal_load((const f32x4*)(base_f + o_)); b1 = __builtin_nontemporal_load((const f32x4*)(base_f + o_ + 4)); }
;                     const f32x4 o0 = b0 + acc[ai][bj][m][0], o1 = b1 + acc[ai][bj][m][1];
;                     if (out_f) { *(f32x4*)(out_f + o_) = o0; *(f32x4*)(out_f + o_ + 4) = o1; }
;                     if (out_b) { u32x4 w; w.x = cvt_pk_bf16(o0[0], o0[1]); w.y = cvt_pk_bf16(o0[2], o0[3]); w.z = cvt_pk_bf16(o1[0], o1[1]); w.w = cvt_pk_bf16(o1[2], o1[3]); *(u32x4*)(out_b + o_) = w; }
;                     sq += ((o0[0] * o0[0] + o0[1] * o0[1]) + (o0[2] * o0[2] + o0[3] * o0[3])) + ((o1[0] * o1[0] + o1[1] * o1[1]) + (o1[2] * o1[2] + o1[3] * o1[3])); }
;                 if (rowsq) { sq += __shfl_xor(sq, 16); sq += __shfl_xor(sq, 32); if (fq == 0) atomicAdd(rowsq + row0 + ai * HALF + m * 16, sq); } }
.LepiA_m7:
	v_pk_add_f32 v[76:77], v[76:77], v[80:81]
	v_pk_add_f32 v[74:75], v[74:75], v[78:79]
	v_pk_add_f32 v[78:79], v[72:73], v[84:85]
	v_mul_f32_e32 v72, v75, v75
	v_mul_f32_e32 v73, v76, v76
	v_mul_f32_e32 v88, v88, v88
	v_pk_add_f32 v[70:71], v[70:71], v[82:83]
	v_fmac_f32_e32 v72, v74, v74
	v_fmac_f32_e32 v73, v77, v77
	v_mul_f32_e32 v92, v101, v101
	v_fmac_f32_e32 v88, v89, v89
	v_mul_f32_e32 v89, v90, v90
	v_mul_f32_e32 v86, v86, v86
	v_add_f32_e32 v72, v72, v73
	v_mul_f32_e32 v73, v70, v70
	v_mul_f32_e32 v80, v78, v78
	v_fmac_f32_e32 v92, v100, v100
	v_fmac_f32_e32 v89, v91, v91
	v_fmac_f32_e32 v86, v87, v87
	v_fmac_f32_e32 v73, v71, v71
	v_fmac_f32_e32 v80, v79, v79
	v_add_f32_e32 v88, v92, v88
	v_add_f32_e32 v86, v86, v89
	v_add_f32_e32 v73, v80, v73
	v_add_f32_e32 v86, v88, v86
	v_add_f32_e32 v72, v72, v73
	v_add_f32_e32 v82, v86, v72
	ds_bpermute_b32 v83, v136, v82
	v_cvt_pk_bf16_f32 v72, v74, v75
	v_cvt_pk_bf16_f32 v73, v76, v77
	v_cvt_pk_bf16_f32 v74, v70, v71
	v_lshlrev_b64 v[80:81], 1, v[94:95]
	s_waitcnt lgkmcnt(0)
	v_add_f32_e32 v70, v82, v83
	ds_bpermute_b32 v71, v137, v70
	v_or_b32_e32 v80, 0x100, v80
	v_lshl_add_u64 v[76:77], s[74:75], 0, v[80:81]
	v_cvt_pk_bf16_f32 v75, v78, v79
	global_store_dwordx4 v[76:77], v[72:75], off
	s_and_saveexec_b64 s[4:5], s[6:7]
	s_cbranch_execz .LBB0_990
	s_waitcnt lgkmcnt(0)
	v_add_f32_e32 v70, v70, v71
	global_atomic_add_f32 v[126:127], v70, off offset:192
.LBB0_990:
	s_or_b64 exec, exec, s[4:5]
	s_mov_b64 s[4:5], 0x20000
	v_lshl_add_u64 v[78:79], v[152:153], 0, s[4:5]
	s_and_b64 vcc, exec, s[10:11]
	v_lshl_add_u64 v[82:83], v[78:79], 1, s[28:29]
	s_cbranch_vccnz .LBB0_1033
	s_nop 1
	v_lshlrev_b32_e32 v70, 16, v208
	s_waitcnt lgkmcnt(0)
	v_and_b32_e32 v71, 0xffff0000, v208
	v_lshlrev_b32_e32 v72, 16, v209
	v_and_b32_e32 v73, 0xffff0000, v209
	v_lshlrev_b32_e32 v74, 16, v210
	v_and_b32_e32 v75, 0xffff0000, v210
	v_lshlrev_b32_e32 v76, 16, v211
	v_and_b32_e32 v77, 0xffff0000, v211
	v_lshl_add_u64 v[80:81], v[78:79], 2, s[12:13]
	s_cbranch_execnz .LepiA_m8
.LBB0_992:
	s_waitcnt lgkmcnt(0)
	v_mov_b32_e32 v226, v80
	v_mov_b32_e32 v227, v81
	global_load_dwordx4 v[176:179], v[226:227], off nt
	global_load_dwordx4 v[180:183], v[226:227], off offset:16 nt
	global_load_dwordx4 v[184:187], v[226:227], off offset:512 nt
	global_load_dwordx4 v[188:191], v[226:227], off offset:528 nt
	v_lshl_add_u64 v[226:227], v[226:227], 0, s[38:39]
	global_load_dwordx4 v[192:195], v[226:227], off nt
	global_load_dwordx4 v[196:199], v[226:227], off offset:16 nt
	global_load_dwordx4 v[200:203], v[226:227], off offset:512 nt
	global_load_dwordx4 v[204:207], v[226:227], off offset:528 nt
	v_lshl_add_u64 v[226:227], v[226:227], 0, s[38:39]
	global_load_dwordx4 v[208:211], v[226:227], off nt
	global_load_dwordx4 v[212:215], v[226:227], off offset:16 nt
	global_load_dwordx4 v[216:219], v[226:227], off offset:512 nt
	global_load_dwordx4 v[220:223], v[226:227], off offset:528 nt
	v_lshl_add_u64 v[226:227], v[226:227], 0, s[38:39]
	global_load_dwordx4 v[236:239], v[226:227], off nt
	global_load_dwordx4 v[240:243], v[226:227], off offset:16 nt
	global_load_dwordx4 v[244:247], v[226:227], off offset:512 nt
	global_load_dwordx4 v[248:251], v[226:227], off offset:528 nt
	s_waitcnt vmcnt(0)
	s_nop 1
	v_mov_b32_e32 v70, v176
	v_mov_b32_e32 v71, v177
	v_mov_b32_e32 v72, v178
	v_mov_b32_e32 v73, v179
	v_mov_b32_e32 v74, v180
	v_mov_b32_e32 v75, v181
	v_mov_b32_e32 v76, v182
	v_mov_b32_e32 v77, v183
	s_branch .LepiA_m8

; __device__ __forceinline__ unsigned cvt_pk_bf16(float lo, float hi) { unsigned r; asm volatile("v_cvt_pk_bf16_f32 %0, %1, %2" : "=v"(r) : "v"(lo), "v"(hi)); return r; }
;     __device__ __forceinline__ void operator()(const f32x4 (&acc)[2][2][4][2], const Unit& u, int wr, int wc, int fr, int fq, const float (&rsv)[8]) const {
;     ...
;                 for (int bj = 0; bj < 2; ++bj) { const size_t o_ = off + bj * HALF; f32x4 b0, b1;
;                     if (base_b) { const u32x4 w = __builtin_nontemporal_load((const u32x4*)(base_b + o_));
;                         b0 = (f32x4){__uint_as_float(w.x << 16), __uint_as_float(w.x & 0xffff0000u), __uint_as_float(w.y << 16), __uint_as_float(w.y & 0xffff0000u)};
;                         b1 = (f32x4){__uint_as_float(w.z << 16), __uint_as_float(w.z & 0xffff0000u), __uint_as_float(w.w << 16), __uint_as_float(w.w & 0xffff0000u)}; }
;                     else { b0 = __builtin_nontemporal_load((const f32x4*)(base_f + o_)); b1 = __builtin_nontemporal_load((const f32x4*)(base_f + o_ + 4)); }
;                     const f32x4 o0 = b0 + acc[ai][bj][m][0], o1 = b1 + acc[ai][bj][m][1];
;                     if (out_f) { *(f32x4*)(out_f + o_) = o0; *(f32x4*)(out_f + o_ + 4) = o1; }
;                     if (out_b) { u32x4 w; w.x = cvt_pk_bf16(o0[0], o0[1]); w.y = cvt_pk_bf16(o0[2], o0[3]); w.z = cvt_pk_bf16(o1[0], o1[1]); w.w = cvt_pk_bf16(o1[2], o1[3]); *(u32x4*)(out_b + o_) = w; }
.LepiA_m8:
	v_pk_add_f32 v[72:73], v[68:69], v[72:73]
	s_waitcnt lgkmcnt(0)
	v_pk_add_f32 v[84:85], v[66:67], v[70:71]
	v_pk_add_f32 v[70:71], v[64:65], v[76:77]
	v_pk_add_f32 v[74:75], v[62:63], v[74:75]
	v_lshl_add_u64 v[66:67], v[78:79], 1, s[74:75]
	s_and_b64 vcc, exec, s[10:11]
	v_cvt_pk_bf16_f32 v62, v84, v85
	v_cvt_pk_bf16_f32 v63, v72, v73
	v_cvt_pk_bf16_f32 v64, v74, v75
	v_cvt_pk_bf16_f32 v65, v70, v71
	global_store_dwordx4 v[66:67], v[62:65], off
	s_cbranch_vccnz .LBB0_1034
	s_nop 1
	v_lshlrev_b32_e32 v62, 16, v212
	v_and_b32_e32 v63, 0xffff0000, v212
	v_lshlrev_b32_e32 v64, 16, v213
	v_and_b32_e32 v65, 0xffff0000, v213
	v_lshlrev_b32_e32 v66, 16, v214
	v_and_b32_e32 v67, 0xffff0000, v214
	v_lshlrev_b32_e32 v68, 16, v215
	v_and_b32_e32 v69, 0xffff0000, v215
	s_cbranch_execnz .LepiA_m9
.LBB0_995:
	s_nop 1
	v_mov_b32_e32 v62, v184
	v_mov_b32_e32 v63, v185
	v_mov_b32_e32 v64, v186
	v_mov_b32_e32 v65, v187
	v_mov_b32_e32 v66, v188
	v_mov_b32_e32 v67, v189
	v_mov_b32_e32 v68, v190
	v_mov_b32_e32 v69, v191
	s_branch .LepiA_m9

; __device__ __forceinline__ unsigned cvt_pk_bf16(float lo, float hi) { unsigned r; asm volatile("v_cvt_pk_bf16_f32 %0, %1, %2" : "=v"(r) : "v"(lo), "v"(hi)); return r; }
;     __device__ __forceinline__ void operator()(const f32x4 (&acc)[2][2][4][2], const Unit& u, int wr, int wc, int fr, int fq, const float (&rsv)[8]) const {
;     ...
;                 for (int bj = 0; bj < 2; ++bj) { const size_t o_ = off + bj * HALF; f32x4 b0, b1;
;                     if (base_b) { const u32x4 w = __builtin_nontemporal_load((const u32x4*)(base_b + o_));
;                         b0 = (f32x4){__uint_as_float(w.x << 16), __uint_as_float(w.x & 0xffff0000u), __uint_as_float(w.y << 16), __uint_as_float(w.y & 0xffff0000u)};
;                         b1 = (f32x4){__uint_as_float(w.z << 16), __uint_as_float(w.z & 0xffff0000u), __uint_as_float(w.w << 16), __uint_as_float(w.w & 0xffff0000u)}; }
;                     else { b0 = __builtin_nontemporal_load((const f32x4*)(base_f + o_)); b1 = __builtin_nontemporal_load((const f32x4*)(base_f + o_ + 4)); }
;                     const f32x4 o0 = b0 + acc[ai][bj][m][0], o1 = b1 + acc[ai][bj][m][1];
;                     if (out_f) { *(f32x4*)(out_f + o_) = o0; *(f32x4*)(out_f + o_ + 4) = o1; }
;                     if (out_b) { u32x4 w; w.x = cvt_pk_bf16(o0[0], o0[1]); w.y = cvt_pk_bf16(o0[2], o0[3]); w.z = cvt_pk_bf16(o1[0], o1[1]); w.w = cvt_pk_bf16(o1[2], o1[3]); *(u32x4*)(out_b + o_) = w; }
;                     sq += ((o0[0] * o0[0] + o0[1] * o0[1]) + (o0[2] * o0[2] + o0[3] * o0[3])) + ((o1[0] * o1[0] + o1[1] * o1[1]) + (o1[2] * o1[2] + o1[3] * o1[3])); }
;                 if (rowsq) { sq += __shfl_xor(sq, 16); sq += __shfl_xor(sq, 32); if (fq == 0) atomicAdd(rowsq + row0 + ai * HALF + m * 16, sq); } }
.LepiA_m9:
	v_pk_add_f32 v[60:61], v[60:61], v[64:65]
	v_pk_add_f32 v[58:59], v[58:59], v[62:63]
	v_pk_add_f32 v[62:63], v[56:57], v[68:69]
	v_mul_f32_e32 v56, v59, v59
	v_mul_f32_e32 v57, v60, v60
	v_mul_f32_e32 v72, v72, v72
	v_pk_add_f32 v[54:55], v[54:55], v[66:67]
	v_fmac_f32_e32 v56, v58, v58
	v_fmac_f32_e32 v57, v61, v61
	v_mul_f32_e32 v76, v85, v85
	v_fmac_f32_e32 v72, v73, v73
	v_mul_f32_e32 v73, v74, v74
	v_mul_f32_e32 v70, v70, v70
	v_add_f32_e32 v56, v56, v57
	v_mul_f32_e32 v57, v54, v54
	v_mul_f32_e32 v64, v62, v62
	v_fmac_f32_e32 v76, v84, v84
	v_fmac_f32_e32 v73, v75, v75
	v_fmac_f32_e32 v70, v71, v71
	v_fmac_f32_e32 v57, v55, v55
	v_fmac_f32_e32 v64, v63, v63
	v_add_f32_e32 v72, v76, v72
	v_add_f32_e32 v70, v70, v73
	v_add_f32_e32 v57, v64, v57
	v_add_f32_e32 v70, v72, v70
	v_add_f32_e32 v56, v56, v57
	v_add_f32_e32 v66, v70, v56
	ds_bpermute_b32 v67, v136, v66
	v_cvt_pk_bf16_f32 v56, v58, v59
	v_cvt_pk_bf16_f32 v57, v60, v61
	v_cvt_pk_bf16_f32 v58, v54, v55
	v_lshlrev_b64 v[64:65], 1, v[78:79]
	s_waitcnt lgkmcnt(0)
	v_add_f32_e32 v54, v66, v67
	ds_bpermute_b32 v55, v137, v54
	v_or_b32_e32 v64, 0x100, v64
	v_lshl_add_u64 v[60:61], s[74:75], 0, v[64:65]
	v_cvt_pk_bf16_f32 v59, v62, v63
	global_store_dwordx4 v[60:61], v[56:59], off
	s_and_saveexec_b64 s[4:5], s[6:7]
	s_cbranch_execz .LBB0_998
	s_waitcnt lgkmcnt(0)
	v_add_f32_e32 v54, v54, v55
	global_atomic_add_f32 v[126:127], v54, off offset:512
.LBB0_998:
	s_or_b64 exec, exec, s[4:5]
	s_mov_b64 s[4:5], 0x24000
	v_lshl_add_u64 v[62:63], v[152:153], 0, s[4:5]
	s_and_b64 vcc, exec, s[10:11]
	v_lshl_add_u64 v[66:67], v[62:63], 1, s[28:29]
	s_cbranch_vccnz .LBB0_1035
	s_nop 1
	v_lshlrev_b32_e32 v54, 16, v216
	s_waitcnt lgkmcnt(0)
	v_and_b32_e32 v55, 0xffff0000, v216
	v_lshlrev_b32_e32 v56, 16, v217
	v_and_b32_e32 v57, 0xffff0000, v217
	v_lshlrev_b32_e32 v58, 16, v218
	v_and_b32_e32 v59, 0xffff0000, v218
	v_lshlrev_b32_e32 v60, 16, v219
	v_and_b32_e32 v61, 0xffff0000, v219
	v_lshl_add_u64 v[64:65], v[62:63], 2, s[12:13]
	s_cbranch_execnz .LepiA_m10
.LBB0_1000:
	s_waitcnt lgkmcnt(0)
	s_nop 1
	v_mov_b32_e32 v54, v192
	v_mov_b32_e32 v55, v193
	v_mov_b32_e32 v56, v194
	v_mov_b32_e32 v57, v195
	v_mov_b32_e32 v58, v196
	v_mov_b32_e32 v59, v197
	v_mov_b32_e32 v60, v198
	v_mov_b32_e32 v61, v199
	s_branch .LepiA_m10

; __device__ __forceinline__ unsigned cvt_pk_bf16(float lo, float hi) { unsigned r; asm volatile("v_cvt_pk_bf16_f32 %0, %1, %2" : "=v"(r) : "v"(lo), "v"(hi)); return r; }
;     __device__ __forceinline__ void operator()(const f32x4 (&acc)[2][2][4][2], const Unit& u, int wr, int wc, int fr, int fq, const float (&rsv)[8]) const {
;     ...
;                 for (int bj = 0; bj < 2; ++bj) { const size_t o_ = off + bj * HALF; f32x4 b0, b1;
;                     if (base_b) { const u32x4 w = __builtin_nontemporal_load((const u32x4*)(base_b + o_));
;                         b0 = (f32x4){__uint_as_float(w.x << 16), __uint_as_float(w.x & 0xffff0000u), __uint_as_float(w.y << 16), __uint_as_float(w.y & 0xffff0000u)};
;                         b1 = (f32x4){__uint_as_float(w.z << 16), __uint_as_float(w.z & 0xffff0000u), __uint_as_float(w.w << 16), __uint_as_float(w.w & 0xffff0000u)}; }
;                     else { b0 = __builtin_nontemporal_load((const f32x4*)(base_f + o_)); b1 = __builtin_nontemporal_load((const f32x4*)(base_f + o_ + 4)); }
;                     const f32x4 o0 = b0 + acc[ai][bj][m][0], o1 = b1 + acc[ai][bj][m][1];
;                     if (out_f) { *(f32x4*)(out_f + o_) = o0; *(f32x4*)(out_f + o_ + 4) = o1; }
;                     if (out_b) { u32x4 w; w.x = cvt_pk_bf16(o0[0], o0[1]); w.y = cvt_pk_bf16(o0[2], o0[3]); w.z = cvt_pk_bf16(o1[0], o1[1]); w.w = cvt_pk_bf16(o1[2], o1[3]); *(u32x4*)(out_b + o_) = w; }
.LepiA_m10:
	v_pk_add_f32 v[56:57], v[52:53], v[56:57]
	s_waitcnt lgkmcnt(0)
	v_pk_add_f32 v[68:69], v[50:51], v[54:55]
	v_pk_add_f32 v[54:55], v[48:49], v[60:61]
	v_pk_add_f32 v[58:59], v[46:47], v[58:59]
	v_lshl_add_u64 v[50:51], v[62:63], 1, s[74:75]
	s_and_b64 vcc, exec, s[10:11]
	v_cvt_pk_bf16_f32 v46, v68, v69
	v_cvt_pk_bf16_f32 v47, v56, v57
	v_cvt_pk_bf16_f32 v48, v58, v59
	v_cvt_pk_bf16_f32 v49, v54, v55
	global_store_dwordx4 v[50:51], v[46:49], off
	s_cbranch_vccnz .LBB0_1036
	s_nop 1
	v_lshlrev_b32_e32 v46, 16, v220
	v_and_b32_e32 v47, 0xffff0000, v220
	v_lshlrev_b32_e32 v48, 16, v221
	v_and_b32_e32 v49, 0xffff0000, v221
	v_lshlrev_b32_e32 v50, 16, v222
	v_and_b32_e32 v51, 0xffff0000, v222
	v_lshlrev_b32_e32 v52, 16, v223
	v_and_b32_e32 v53, 0xffff0000, v223
	s_cbranch_execnz .LepiA_m11
.LBB0_1003:
	s_nop 1
	v_mov_b32_e32 v46, v200
	v_mov_b32_e32 v47, v201
	v_mov_b32_e32 v48, v202
	v_mov_b32_e32 v49, v203
	v_mov_b32_e32 v50, v204
	v_mov_b32_e32 v51, v205
	v_mov_b32_e32 v52, v206
	v_mov_b32_e32 v53, v207
	s_branch .LepiA_m11

; __device__ __forceinline__ unsigned cvt_pk_bf16(float lo, float hi) { unsigned r; asm volatile("v_cvt_pk_bf16_f32 %0, %1, %2" : "=v"(r) : "v"(lo), "v"(hi)); return r; }
;     __device__ __forceinline__ void operator()(const f32x4 (&acc)[2][2][4][2], const Unit& u, int wr, int wc, int fr, int fq, const float (&rsv)[8]) const {
;     ...
;                 for (int bj = 0; bj < 2; ++bj) { const size_t o_ = off + bj * HALF; f32x4 b0, b1;
;                     if (base_b) { const u32x4 w = __builtin_nontemporal_load((const u32x4*)(base_b + o_));
;                         b0 = (f32x4){__uint_as_float(w.x << 16), __uint_as_float(w.x & 0xffff0000u), __uint_as_float(w.y << 16), __uint_as_float(w.y & 0xffff0000u)};
;                         b1 = (f32x4){__uint_as_float(w.z << 16), __uint_as_float(w.z & 0xffff0000u), __uint_as_float(w.w << 16), __uint_as_float(w.w & 0xffff0000u)}; }
;                     else { b0 = __builtin_nontemporal_load((const f32x4*)(base_f + o_)); b1 = __builtin_nontemporal_load((const f32x4*)(base_f + o_ + 4)); }
;                     const f32x4 o0 = b0 + acc[ai][bj][m][0], o1 = b1 + acc[ai][bj][m][1];
;                     if (out_f) { *(f32x4*)(out_f + o_) = o0; *(f32x4*)(out_f + o_ + 4) = o1; }
;                     if (out_b) { u32x4 w; w.x = cvt_pk_bf16(o0[0], o0[1]); w.y = cvt_pk_bf16(o0[2], o0[3]); w.z = cvt_pk_bf16(o1[0], o1[1]); w.w = cvt_pk_bf16(o1[2], o1[3]); *(u32x4*)(out_b + o_) = w; }
;                     sq += ((o0[0] * o0[0] + o0[1] * o0[1]) + (o0[2] * o0[2] + o0[3] * o0[3])) + ((o1[0] * o1[0] + o1[1] * o1[1]) + (o1[2] * o1[2] + o1[3] * o1[3])); }
;                 if (rowsq) { sq += __shfl_xor(sq, 16); sq += __shfl_xor(sq, 32); if (fq == 0) atomicAdd(rowsq + row0 + ai * HALF + m * 16, sq); } }
.LepiA_m11:
	v_pk_add_f32 v[44:45], v[44:45], v[48:49]
	v_pk_add_f32 v[42:43], v[42:43], v[46:47]
	v_pk_add_f32 v[46:47], v[40:41], v[52:53]
	v_mul_f32_e32 v40, v43, v43
	v_mul_f32_e32 v41, v44, v44
	v_mul_f32_e32 v56, v56, v56
	v_pk_add_f32 v[38:39], v[38:39], v[50:51]
	v_fmac_f32_e32 v40, v42, v42
	v_fmac_f32_e32 v41, v45, v45
	v_mul_f32_e32 v60, v69, v69
	v_fmac_f32_e32 v56, v57, v57
	v_mul_f32_e32 v57, v58, v58
	v_mul_f32_e32 v54, v54, v54
	v_add_f32_e32 v40, v40, v41
	v_mul_f32_e32 v41, v38, v38
	v_mul_f32_e32 v48, v46, v46
	v_fmac_f32_e32 v60, v68, v68
	v_fmac_f32_e32 v57, v59, v59
	v_fmac_f32_e32 v54, v55, v55
	v_fmac_f32_e32 v41, v39, v39
	v_fmac_f32_e32 v48, v47, v47
	v_add_f32_e32 v56, v60, v56
	v_add_f32_e32 v54, v54, v57
	v_add_f32_e32 v41, v48, v41
	v_add_f32_e32 v54, v56, v54
	v_add_f32_e32 v40, v40, v41
	v_add_f32_e32 v50, v54, v40
	ds_bpermute_b32 v51, v136, v50
	v_cvt_pk_bf16_f32 v40, v42, v43
	v_cvt_pk_bf16_f32 v41, v44, v45
	v_cvt_pk_bf16_f32 v42, v38, v39
	v_lshlrev_b64 v[48:49], 1, v[62:63]
	s_waitcnt lgkmcnt(0)
	v_add_f32_e32 v38, v50, v51
	ds_bpermute_b32 v39, v137, v38
	v_or_b32_e32 v48, 0x100, v48
	v_lshl_add_u64 v[44:45], s[74:75], 0, v[48:49]
	v_cvt_pk_bf16_f32 v43, v46, v47
	global_store_dwordx4 v[44:45], v[40:43], off
	s_and_saveexec_b64 s[4:5], s[6:7]
	s_cbranch_execz .LBB0_1006
	s_waitcnt lgkmcnt(0)
	v_add_f32_e32 v38, v38, v39
	global_atomic_add_f32 v[126:127], v38, off offset:576
.LBB0_1006:
	s_or_b64 exec, exec, s[4:5]
	s_mov_b64 s[4:5], 0x28000
	v_lshl_add_u64 v[46:47], v[152:153], 0, s[4:5]
	s_and_b64 vcc, exec, s[10:11]
	v_lshl_add_u64 v[50:51], v[46:47], 1, s[28:29]
	s_cbranch_vccnz .LBB0_1037
	s_nop 1
	v_lshlrev_b32_e32 v38, 16, v236
	s_waitcnt lgkmcnt(0)
	v_and_b32_e32 v39, 0xffff0000, v236
	v_lshlrev_b32_e32 v40, 16, v237
	v_and_b32_e32 v41, 0xffff0000, v237
	v_lshlrev_b32_e32 v42, 16, v238
	v_and_b32_e32 v43, 0xffff0000, v238
	v_lshlrev_b32_e32 v44, 16, v239
	v_and_b32_e32 v45, 0xffff0000, v239
	v_lshl_add_u64 v[48:49], v[46:47], 2, s[12:13]
	s_cbranch_execnz .LepiA_m12
.LBB0_1008:
	s_waitcnt lgkmcnt(0)
	s_nop 1
	v_mov_b32_e32 v38, v208
	v_mov_b32_e32 v39, v209
	v_mov_b32_e32 v40, v210
	v_mov_b32_e32 v41, v211
	v_mov_b32_e32 v42, v212
	v_mov_b32_e32 v43, v213
	v_mov_b32_e32 v44, v214
	v_mov_b32_e32 v45, v215
	s_branch .LepiA_m12

; __device__ __forceinline__ unsigned cvt_pk_bf16(float lo, float hi) { unsigned r; asm volatile("v_cvt_pk_bf16_f32 %0, %1, %2" : "=v"(r) : "v"(lo), "v"(hi)); return r; }
;     __device__ __forceinline__ void operator()(const f32x4 (&acc)[2][2][4][2], const Unit& u, int wr, int wc, int fr, int fq, const float (&rsv)[8]) const {
;     ...
;                 for (int bj = 0; bj < 2; ++bj) { const size_t o_ = off + bj * HALF; f32x4 b0, b1;
;                     if (base_b) { const u32x4 w = __builtin_nontemporal_load((const u32x4*)(base_b + o_));
;                         b0 = (f32x4){__uint_as_float(w.x << 16), __uint_as_float(w.x & 0xffff0000u), __uint_as_float(w.y << 16), __uint_as_float(w.y & 0xffff0000u)};
;                         b1 = (f32x4){__uint_as_float(w.z << 16), __uint_as_float(w.z & 0xffff0000u), __uint_as_float(w.w << 16), __uint_as_float(w.w & 0xffff0000u)}; }
;                     else { b0 = __builtin_nontemporal_load((const f32x4*)(base_f + o_)); b1 = __builtin_nontemporal_load((const f32x4*)(base_f + o_ + 4)); }
;                     const f32x4 o0 = b0 + acc[ai][bj][m][0], o1 = b1 + acc[ai][bj][m][1];
;                     if (out_f) { *(f32x4*)(out_f + o_) = o0; *(f32x4*)(out_f + o_ + 4) = o1; }
;                     if (out_b) { u32x4 w; w.x = cvt_pk_bf16(o0[0], o0[1]); w.y = cvt_pk_bf16(o0[2], o0[3]); w.z = cvt_pk_bf16(o1[0], o1[1]); w.w = cvt_pk_bf16(o1[2], o1[3]); *(u32x4*)(out_b + o_) = w; }
.LepiA_m12:
	v_pk_add_f32 v[40:41], v[36:37], v[40:41]
	s_waitcnt lgkmcnt(0)
	v_pk_add_f32 v[52:53], v[34:35], v[38:39]
	v_pk_add_f32 v[38:39], v[32:33], v[44:45]
	v_pk_add_f32 v[42:43], v[30:31], v[42:43]
	v_lshl_add_u64 v[34:35], v[46:47], 1, s[74:75]
	s_and_b64 vcc, exec, s[10:11]
	v_cvt_pk_bf16_f32 v30, v52, v53
	v_cvt_pk_bf16_f32 v31, v40, v41
	v_cvt_pk_bf16_f32 v32, v42, v43
	v_cvt_pk_bf16_f32 v33, v38, v39
	global_store_dwordx4 v[34:35], v[30:33], off
	s_cbranch_vccnz .LBB0_1038
	s_nop 1
	v_lshlrev_b32_e32 v30, 16, v240
	v_and_b32_e32 v31, 0xffff0000, v240
	v_lshlrev_b32_e32 v32, 16, v241
	v_and_b32_e32 v33, 0xffff0000, v241
	v_lshlrev_b32_e32 v34, 16, v242
	v_and_b32_e32 v35, 0xffff0000, v242
	v_lshlrev_b32_e32 v36, 16, v243
	v_and_b32_e32 v37, 0xffff0000, v243
	s_cbranch_execnz .LepiA_m13
.LBB0_1011:
	s_nop 1
	v_mov_b32_e32 v30, v216
	v_mov_b32_e32 v31, v217
	v_mov_b32_e32 v32, v218
	v_mov_b32_e32 v33, v219
	v_mov_b32_e32 v34, v220
	v_mov_b32_e32 v35, v221
	v_mov_b32_e32 v36, v222
	v_mov_b32_e32 v37, v223
	s_branch .LepiA_m13

; __device__ __forceinline__ unsigned cvt_pk_bf16(float lo, float hi) { unsigned r; asm volatile("v_cvt_pk_bf16_f32 %0, %1, %2" : "=v"(r) : "v"(lo), "v"(hi)); return r; }
;     __device__ __forceinline__ void operator()(const f32x4 (&acc)[2][2][4][2], const Unit& u, int wr, int wc, int fr, int fq, const float (&rsv)[8]) const {
;     ...
;                 for (int bj = 0; bj < 2; ++bj) { const size_t o_ = off + bj * HALF; f32x4 b0, b1;
;                     if (base_b) { const u32x4 w = __builtin_nontemporal_load((const u32x4*)(base_b + o_));
;                         b0 = (f32x4){__uint_as_float(w.x << 16), __uint_as_float(w.x & 0xffff0000u), __uint_as_float(w.y << 16), __uint_as_float(w.y & 0xffff0000u)};
;                         b1 = (f32x4){__uint_as_float(w.z << 16), __uint_as_float(w.z & 0xffff0000u), __uint_as_float(w.w << 16), __uint_as_float(w.w & 0xffff0000u)}; }
;                     else { b0 = __builtin_nontemporal_load((const f32x4*)(base_f + o_)); b1 = __builtin_nontemporal_load((const f32x4*)(base_f + o_ + 4)); }
;                     const f32x4 o0 = b0 + acc[ai][bj][m][0], o1 = b1 + acc[ai][bj][m][1];
;                     if (out_f) { *(f32x4*)(out_f + o_) = o0; *(f32x4*)(out_f + o_ + 4) = o1; }
;                     if (out_b) { u32x4 w; w.x = cvt_pk_bf16(o0[0], o0[1]); w.y = cvt_pk_bf16(o0[2], o0[3]); w.z = cvt_pk_bf16(o1[0], o1[1]); w.w = cvt_pk_bf16(o1[2], o1[3]); *(u32x4*)(out_b + o_) = w; }
;                     sq += ((o0[0] * o0[0] + o0[1] * o0[1]) + (o0[2] * o0[2] + o0[3] * o0[3])) + ((o1[0] * o1[0] + o1[1] * o1[1]) + (o1[2] * o1[2] + o1[3] * o1[3])); }
;                 if (rowsq) { sq += __shfl_xor(sq, 16); sq += __shfl_xor(sq, 32); if (fq == 0) atomicAdd(rowsq + row0 + ai * HALF + m * 16, sq); } }
.LepiA_m13:
	v_pk_add_f32 v[28:29], v[28:29], v[32:33]
	v_pk_add_f32 v[26:27], v[26:27], v[30:31]
	v_pk_add_f32 v[30:31], v[24:25], v[36:37]
	v_mul_f32_e32 v24, v27, v27
	v_mul_f32_e32 v25, v28, v28
	v_mul_f32_e32 v40, v40, v40
	v_pk_add_f32 v[22:23], v[22:23], v[34:35]
	v_fmac_f32_e32 v24, v26, v26
	v_fmac_f32_e32 v25, v29, v29
	v_mul_f32_e32 v44, v53, v53
	v_fmac_f32_e32 v40, v41, v41
	v_mul_f32_e32 v41, v42, v42
	v_mul_f32_e32 v38, v38, v38
	v_add_f32_e32 v24, v24, v25
	v_mul_f32_e32 v25, v22, v22
	v_mul_f32_e32 v32, v30, v30
	v_fmac_f32_e32 v44, v52, v52
	v_fmac_f32_e32 v41, v43, v43
	v_fmac_f32_e32 v38, v39, v39
	v_fmac_f32_e32 v25, v23, v23
	v_fmac_f32_e32 v32, v31, v31
	v_add_f32_e32 v40, v44, v40
	v_add_f32_e32 v38, v38, v41
	v_add_f32_e32 v25, v32, v25
	v_add_f32_e32 v38, v40, v38
	v_add_f32_e32 v24, v24, v25
	v_add_f32_e32 v34, v38, v24
	ds_bpermute_b32 v35, v136, v34
	v_cvt_pk_bf16_f32 v24, v26, v27
	v_cvt_pk_bf16_f32 v25, v28, v29
	v_cvt_pk_bf16_f32 v26, v22, v23
	v_lshlrev_b64 v[32:33], 1, v[46:47]
	s_waitcnt lgkmcnt(0)
	v_add_f32_e32 v22, v34, v35
	ds_bpermute_b32 v23, v137, v22
	v_or_b32_e32 v32, 0x100, v32
	v_lshl_add_u64 v[28:29], s[74:75], 0, v[32:33]
	v_cvt_pk_bf16_f32 v27, v30, v31
	global_store_dwordx4 v[28:29], v[24:27], off
	s_and_saveexec_b64 s[4:5], s[6:7]
	s_cbranch_execz .LBB0_1014
	s_waitcnt lgkmcnt(0)
	v_add_f32_e32 v22, v22, v23
	global_atomic_add_f32 v[126:127], v22, off offset:640
.LBB0_1014:
	s_or_b64 exec, exec, s[4:5]
	s_mov_b64 s[4:5], 0x2c000
	v_lshl_add_u64 v[30:31], v[152:153], 0, s[4:5]
	s_and_b64 vcc, exec, s[10:11]
	v_lshl_add_u64 v[34:35], v[30:31], 1, s[28:29]
	s_cbranch_vccnz .LBB0_1039
	s_nop 1
	v_lshlrev_b32_e32 v22, 16, v244
	s_waitcnt lgkmcnt(0)
	v_and_b32_e32 v23, 0xffff0000, v244
	v_lshlrev_b32_e32 v24, 16, v245
	v_and_b32_e32 v25, 0xffff0000, v245
	v_lshlrev_b32_e32 v26, 16, v246
	v_and_b32_e32 v27, 0xffff0000, v246
	v_lshlrev_b32_e32 v28, 16, v247
	v_and_b32_e32 v29, 0xffff0000, v247
	v_lshl_add_u64 v[32:33], v[30:31], 2, s[12:13]
	s_cbranch_execnz .LepiA_m14
.LBB0_1016:
	s_waitcnt lgkmcnt(0)
	s_nop 1
	v_mov_b32_e32 v22, v236
	v_mov_b32_e32 v23, v237
	v_mov_b32_e32 v24, v238
	v_mov_b32_e32 v25, v239
	v_mov_b32_e32 v26, v240
	v_mov_b32_e32 v27, v241
	v_mov_b32_e32 v28, v242
	v_mov_b32_e32 v29, v243
	s_branch .LepiA_m14

; __device__ __forceinline__ unsigned cvt_pk_bf16(float lo, float hi) { unsigned r; asm volatile("v_cvt_pk_bf16_f32 %0, %1, %2" : "=v"(r) : "v"(lo), "v"(hi)); return r; }
;     __device__ __forceinline__ void operator()(const f32x4 (&acc)[2][2][4][2], const Unit& u, int wr, int wc, int fr, int fq, const float (&rsv)[8]) const {
;     ...
;                 for (int bj = 0; bj < 2; ++bj) { const size_t o_ = off + bj * HALF; f32x4 b0, b1;
;                     if (base_b) { const u32x4 w = __builtin_nontemporal_load((const u32x4*)(base_b + o_));
;                         b0 = (f32x4){__uint_as_float(w.x << 16), __uint_as_float(w.x & 0xffff0000u), __uint_as_float(w.y << 16), __uint_as_float(w.y & 0xffff0000u)};
;                         b1 = (f32x4){__uint_as_float(w.z << 16), __uint_as_float(w.z & 0xffff0000u), __uint_as_float(w.w << 16), __uint_as_float(w.w & 0xffff0000u)}; }
;                     else { b0 = __builtin_nontemporal_load((const f32x4*)(base_f + o_)); b1 = __builtin_nontemporal_load((const f32x4*)(base_f + o_ + 4)); }
;                     const f32x4 o0 = b0 + acc[ai][bj][m][0], o1 = b1 + acc[ai][bj][m][1];
;                     if (out_f) { *(f32x4*)(out_f + o_) = o0; *(f32x4*)(out_f + o_ + 4) = o1; }
;                     if (out_b) { u32x4 w; w.x = cvt_pk_bf16(o0[0], o0[1]); w.y = cvt_pk_bf16(o0[2], o0[3]); w.z = cvt_pk_bf16(o1[0], o1[1]); w.w = cvt_pk_bf16(o1[2], o1[3]); *(u32x4*)(out_b + o_) = w; }
.LepiA_m14:
	v_pk_add_f32 v[24:25], v[20:21], v[24:25]
	s_waitcnt lgkmcnt(0)
	v_pk_add_f32 v[36:37], v[18:19], v[22:23]
	v_pk_add_f32 v[22:23], v[16:17], v[28:29]
	v_pk_add_f32 v[26:27], v[14:15], v[26:27]
	v_lshl_add_u64 v[18:19], v[30:31], 1, s[74:75]
	s_and_b64 vcc, exec, s[10:11]
	v_cvt_pk_bf16_f32 v14, v36, v37
	v_cvt_pk_bf16_f32 v15, v24, v25
	v_cvt_pk_bf16_f32 v16, v26, v27
	v_cvt_pk_bf16_f32 v17, v22, v23
	global_store_dwordx4 v[18:19], v[14:17], off
	s_cbranch_vccnz .LBB0_1040
	s_nop 1
	v_lshlrev_b32_e32 v14, 16, v248
	v_and_b32_e32 v15, 0xffff0000, v248
	v_lshlrev_b32_e32 v16, 16, v249
	v_and_b32_e32 v17, 0xffff0000, v249
	v_lshlrev_b32_e32 v18, 16, v250
	v_and_b32_e32 v19, 0xffff0000, v250
	v_lshlrev_b32_e32 v20, 16, v251
	v_and_b32_e32 v21, 0xffff0000, v251
	s_cbranch_execnz .LepiA_m15
.LBB0_1019:
	s_nop 1
	v_mov_b32_e32 v14, v244
	v_mov_b32_e32 v15, v245
	v_mov_b32_e32 v16, v246
	v_mov_b32_e32 v17, v247
	v_mov_b32_e32 v18, v248
	v_mov_b32_e32 v19, v249
	v_mov_b32_e32 v20, v250
	v_mov_b32_e32 v21, v251
	s_branch .LepiA_m15

; __device__ __forceinline__ unsigned cvt_pk_bf16(float lo, float hi) { unsigned r; asm volatile("v_cvt_pk_bf16_f32 %0, %1, %2" : "=v"(r) : "v"(lo), "v"(hi)); return r; }
;     __device__ __forceinline__ void operator()(const f32x4 (&acc)[2][2][4][2], const Unit& u, int wr, int wc, int fr, int fq, const float (&rsv)[8]) const {
;     ...
;                     const f32x4 o0 = b0 + acc[ai][bj][m][0], o1 = b1 + acc[ai][bj][m][1];
;                     if (out_f) { *(f32x4*)(out_f + o_) = o0; *(f32x4*)(out_f + o_ + 4) = o1; }
;                     if (out_b) { u32x4 w; w.x = cvt_pk_bf16(o0[0], o0[1]); w.y = cvt_pk_bf16(o0[2], o0[3]); w.z = cvt_pk_bf16(o1[0], o1[1]); w.w = cvt_pk_bf16(o1[2], o1[3]); *(u32x4*)(out_b + o_) = w; }
;                     sq += ((o0[0] * o0[0] + o0[1] * o0[1]) + (o0[2] * o0[2] + o0[3] * o0[3])) + ((o1[0] * o1[0] + o1[1] * o1[1]) + (o1[2] * o1[2] + o1[3] * o1[3])); }
;                 if (rowsq) { sq += __shfl_xor(sq, 16); sq += __shfl_xor(sq, 32); if (fq == 0) atomicAdd(rowsq + row0 + ai * HALF + m * 16, sq); } }
.LepiA_m15:
	v_pk_add_f32 v[12:13], v[12:13], v[16:17]
	v_pk_add_f32 v[10:11], v[10:11], v[14:15]
	v_pk_add_f32 v[14:15], v[8:9], v[20:21]
	v_mul_f32_e32 v8, v11, v11
	v_mul_f32_e32 v9, v12, v12
	v_mul_f32_e32 v24, v24, v24
	v_pk_add_f32 v[6:7], v[6:7], v[18:19]
	v_fmac_f32_e32 v8, v10, v10
	v_fmac_f32_e32 v9, v13, v13
	v_mul_f32_e32 v28, v37, v37
	v_fmac_f32_e32 v24, v25, v25
	v_mul_f32_e32 v25, v26, v26
	v_mul_f32_e32 v22, v22, v22
	v_add_f32_e32 v8, v8, v9
	v_mul_f32_e32 v9, v6, v6
	v_mul_f32_e32 v16, v14, v14
	v_fmac_f32_e32 v28, v36, v36
	v_fmac_f32_e32 v25, v27, v27
	v_fmac_f32_e32 v22, v23, v23
	v_fmac_f32_e32 v9, v7, v7
	v_fmac_f32_e32 v16, v15, v15
	v_add_f32_e32 v24, v28, v24
	v_add_f32_e32 v22, v22, v25
	v_add_f32_e32 v9, v16, v9
	v_add_f32_e32 v22, v24, v22
	v_add_f32_e32 v8, v8, v9
	v_add_f32_e32 v18, v22, v8
	ds_bpermute_b32 v19, v136, v18
	v_cvt_pk_bf16_f32 v8, v10, v11
	v_cvt_pk_bf16_f32 v9, v12, v13
	v_cvt_pk_bf16_f32 v10, v6, v7
	v_lshlrev_b64 v[16:17], 1, v[30:31]
	s_waitcnt lgkmcnt(0)
	v_add_f32_e32 v6, v18, v19
	ds_bpermute_b32 v7, v137, v6
	v_or_b32_e32 v16, 0x100, v16
	v_lshl_add_u64 v[12:13], s[74:75], 0, v[16:17]
	v_cvt_pk_bf16_f32 v11, v14, v15
	global_store_dwordx4 v[12:13], v[8:11], off
	s_and_saveexec_b64 s[4:5], s[6:7]
	s_cbranch_execz .LBB0_1022
	s_waitcnt lgkmcnt(0)
	v_add_f32_e32 v6, v6, v7
	global_atomic_add_f32 v[126:127], v6, off offset:704

;     __device__ __forceinline__ void operator()(const f32x4 (&acc)[2][2][4][2], const Unit& u, int wr, int wc, int fr, int fq, const float (&rsv)[8]) const {
;     ...
;             for (int m = 0; m < 4; ++m) { const size_t off = (size_t)(row0 + ai * HALF + m * 16) * ldc + col0; float sq = 0.f;
; #pragma unroll
;                 for (int bj = 0; bj < 2; ++bj) { const size_t o_ = off + bj * HALF; f32x4 b0, b1;
;                     if (base_b) { const u32x4 w = __builtin_nontemporal_load((const u32x4*)(base_b + o_));
;                         b0 = (f32x4){__uint_as_float(w.x << 16), __uint_as_float(w.x & 0xffff0000u), __uint_as_float(w.y << 16), __uint_as_float(w.y & 0xffff0000u)};
;                         b1 = (f32x4){__uint_as_float(w.z << 16), __uint_as_float(w.z & 0xffff0000u), __uint_as_float(w.w << 16), __uint_as_float(w.w & 0xffff0000u)}; }
;                     else { b0 = __builtin_nontemporal_load((const f32x4*)(base_f + o_)); b1 = __builtin_nontemporal_load((const f32x4*)(base_f + o_ + 4)); }
;                     const f32x4 o0 = b0 + acc[ai][bj][m][0], o1 = b1 + acc[ai][bj][m][1];
;                     if (out_f) { *(f32x4*)(out_f + o_) = o0; *(f32x4*)(out_f + o_ + 4) = o1; }
.LBB0_1184:
	v_lshl_add_u32 v144, s81, 8, v155
	v_lshl_or_b32 v148, s37, 8, v163
	v_ashrrev_i32_e32 v145, 31, v144
	v_ashrrev_i32_e32 v149, 31, v148
	v_lshlrev_b64 v[146:147], 10, v[144:145]
	v_lshl_add_u64 v[146:147], v[146:147], 0, v[148:149]
	v_lshl_add_u64 v[150:151], v[146:147], 1, s[74:75]
	v_mov_b32_e32 v174, v150
	v_mov_b32_e32 v175, v151
	s_mov_b64 s[40:41], 0x8000
	s_mov_b64 s[44:45], 0x28000
	global_load_dwordx4 v[176:179], v[174:175], off nt
	global_load_dwordx4 v[180:183], v[174:175], off offset:256 nt
	v_lshl_add_u64 v[174:175], v[174:175], 0, s[40:41]
	global_load_dwordx4 v[184:187], v[174:175], off nt
	global_load_dwordx4 v[188:191], v[174:175], off offset:256 nt
	v_lshl_add_u64 v[174:175], v[174:175], 0, s[40:41]
	global_load_dwordx4 v[192:195], v[174:175], off nt
	global_load_dwordx4 v[196:199], v[174:175], off offset:256 nt
	v_lshl_add_u64 v[174:175], v[174:175], 0, s[40:41]
	global_load_dwordx4 v[200:203], v[174:175], off nt
	global_load_dwordx4 v[204:207], v[174:175], off offset:256 nt
	v_lshl_add_u64 v[174:175], v[174:175], 0, s[44:45]
	global_load_dwordx4 v[208:211], v[174:175], off nt
	global_load_dwordx4 v[212:215], v[174:175], off offset:256 nt
	v_lshl_add_u64 v[174:175], v[174:175], 0, s[40:41]
	global_load_dwordx4 v[216:219], v[174:175], off nt
	global_load_dwordx4 v[220:223], v[174:175], off offset:256 nt
	v_lshl_add_u64 v[174:175], v[174:175], 0, s[40:41]
	s_waitcnt vmcnt(0)
	v_cndmask_b32_e64 v165, 0, 1, s[20:21]
	v_cmp_ne_u32_e64 s[8:9], 1, v165
	s_andn2_b64 vcc, exec, s[20:21]
	v_lshlrev_b32_e32 v166, 16, v176
	v_and_b32_e32 v167, 0xffff0000, v176
	v_lshlrev_b32_e32 v150, 16, v177
	v_and_b32_e32 v151, 0xffff0000, v177
	v_lshlrev_b32_e32 v168, 16, v178
	v_and_b32_e32 v169, 0xffff0000, v178
	v_lshlrev_b32_e32 v152, 16, v179
	v_and_b32_e32 v153, 0xffff0000, v179
	v_pk_add_f32 v[132:133], v[132:133], v[150:151]
	v_pk_add_f32 v[130:131], v[130:131], v[166:167]
	v_pk_add_f32 v[128:129], v[128:129], v[152:153]
	v_pk_add_f32 v[126:127], v[126:127], v[168:169]
	v_lshl_add_u64 v[152:153], v[146:147], 2, s[34:35]
	s_cbranch_vccnz .LBB0_1186
	global_store_dwordx4 v[152:153], v[130:133], off
	global_store_dwordx4 v[152:153], v[126:129], off offset:16

; __device__ __forceinline__ unsigned cvt_pk_bf16(float lo, float hi) { unsigned r; asm volatile("v_cvt_pk_bf16_f32 %0, %1, %2" : "=v"(r) : "v"(lo), "v"(hi)); return r; }
;     __device__ __forceinline__ void operator()(const f32x4 (&acc)[2][2][4][2], const Unit& u, int wr, int wc, int fr, int fq, const float (&rsv)[8]) const {
;     ...
;                 for (int bj = 0; bj < 2; ++bj) { const size_t o_ = off + bj * HALF; f32x4 b0, b1;
;                     if (base_b) { const u32x4 w = __builtin_nontemporal_load((const u32x4*)(base_b + o_));
;                         b0 = (f32x4){__uint_as_float(w.x << 16), __uint_as_float(w.x & 0xffff0000u), __uint_as_float(w.y << 16), __uint_as_float(w.y & 0xffff0000u)};
;                         b1 = (f32x4){__uint_as_float(w.z << 16), __uint_as_float(w.z & 0xffff0000u), __uint_as_float(w.w << 16), __uint_as_float(w.w & 0xffff0000u)}; }
;                     else { b0 = __builtin_nontemporal_load((const f32x4*)(base_f + o_)); b1 = __builtin_nontemporal_load((const f32x4*)(base_f + o_ + 4)); }
;                     const f32x4 o0 = b0 + acc[ai][bj][m][0], o1 = b1 + acc[ai][bj][m][1];
;                     if (out_f) { *(f32x4*)(out_f + o_) = o0; *(f32x4*)(out_f + o_ + 4) = o1; }
;                     if (out_b) { u32x4 w; w.x = cvt_pk_bf16(o0[0], o0[1]); w.y = cvt_pk_bf16(o0[2], o0[3]); w.z = cvt_pk_bf16(o1[0], o1[1]); w.w = cvt_pk_bf16(o1[2], o1[3]); *(u32x4*)(out_b + o_) = w; }
.LBB0_1190:
	s_nop 1
	v_lshlrev_b64 v[166:167], 1, v[146:147]
	v_or_b32_e32 v166, 0x100, v166
	v_lshl_add_u64 v[166:167], s[74:75], 0, v[166:167]
	s_nop 1
	s_and_b64 vcc, exec, s[8:9]
	v_lshlrev_b32_e32 v170, 16, v180
	v_and_b32_e32 v171, 0xffff0000, v180
	v_lshlrev_b32_e32 v166, 16, v181
	v_and_b32_e32 v167, 0xffff0000, v181
	v_lshlrev_b32_e32 v172, 16, v182
	v_and_b32_e32 v173, 0xffff0000, v182
	v_lshlrev_b32_e32 v168, 16, v183
	v_and_b32_e32 v169, 0xffff0000, v183
	v_pk_add_f32 v[124:125], v[124:125], v[166:167]
	v_pk_add_f32 v[122:123], v[122:123], v[170:171]
	v_pk_add_f32 v[120:121], v[120:121], v[168:169]
	v_pk_add_f32 v[118:119], v[118:119], v[172:173]
	s_cbranch_vccnz .LBB0_1192
	global_store_dwordx4 v[152:153], v[122:125], off offset:512
	global_store_dwordx4 v[152:153], v[118:121], off offset:528

; __device__ __forceinline__ unsigned cvt_pk_bf16(float lo, float hi) { unsigned r; asm volatile("v_cvt_pk_bf16_f32 %0, %1, %2" : "=v"(r) : "v"(lo), "v"(hi)); return r; }
;     __device__ __forceinline__ void operator()(const f32x4 (&acc)[2][2][4][2], const Unit& u, int wr, int wc, int fr, int fq, const float (&rsv)[8]) const {
;     ...
;                 for (int bj = 0; bj < 2; ++bj) { const size_t o_ = off + bj * HALF; f32x4 b0, b1;
;                     if (base_b) { const u32x4 w = __builtin_nontemporal_load((const u32x4*)(base_b + o_));
;                         b0 = (f32x4){__uint_as_float(w.x << 16), __uint_as_float(w.x & 0xffff0000u), __uint_as_float(w.y << 16), __uint_as_float(w.y & 0xffff0000u)};
;                         b1 = (f32x4){__uint_as_float(w.z << 16), __uint_as_float(w.z & 0xffff0000u), __uint_as_float(w.w << 16), __uint_as_float(w.w & 0xffff0000u)}; }
;                     else { b0 = __builtin_nontemporal_load((const f32x4*)(base_f + o_)); b1 = __builtin_nontemporal_load((const f32x4*)(base_f + o_ + 4)); }
;                     const f32x4 o0 = b0 + acc[ai][bj][m][0], o1 = b1 + acc[ai][bj][m][1];
;                     if (out_f) { *(f32x4*)(out_f + o_) = o0; *(f32x4*)(out_f + o_ + 4) = o1; }
;                     if (out_b) { u32x4 w; w.x = cvt_pk_bf16(o0[0], o0[1]); w.y = cvt_pk_bf16(o0[2], o0[3]); w.z = cvt_pk_bf16(o1[0], o1[1]); w.w = cvt_pk_bf16(o1[2], o1[3]); *(u32x4*)(out_b + o_) = w; }
.LBB0_1200:
	v_or_b32_e32 v118, 16, v144
	s_waitcnt lgkmcnt(0)
	v_ashrrev_i32_e32 v119, 31, v118
	v_lshlrev_b64 v[118:119], 10, v[118:119]
	v_lshl_add_u64 v[122:123], v[118:119], 0, v[148:149]
	v_lshl_add_u64 v[118:119], v[122:123], 1, s[74:75]
	s_nop 1
	s_and_b64 vcc, exec, s[8:9]
	v_lshlrev_b32_e32 v124, 16, v184
	v_and_b32_e32 v125, 0xffff0000, v184
	v_lshlrev_b32_e32 v118, 16, v185
	v_and_b32_e32 v119, 0xffff0000, v185
	v_lshlrev_b32_e32 v126, 16, v186
	v_and_b32_e32 v127, 0xffff0000, v186
	v_lshlrev_b32_e32 v120, 16, v187
	v_and_b32_e32 v121, 0xffff0000, v187
	v_pk_add_f32 v[116:117], v[116:117], v[118:119]
	v_pk_add_f32 v[114:115], v[114:115], v[124:125]
	v_pk_add_f32 v[112:113], v[112:113], v[120:121]
	v_pk_add_f32 v[110:111], v[110:111], v[126:127]
	v_lshl_add_u64 v[120:121], v[122:123], 2, s[34:35]
	s_cbranch_vccnz .LBB0_1202
	global_store_dwordx4 v[120:121], v[114:117], off
	global_store_dwordx4 v[120:121], v[110:113], off offset:16

; __device__ __forceinline__ unsigned cvt_pk_bf16(float lo, float hi) { unsigned r; asm volatile("v_cvt_pk_bf16_f32 %0, %1, %2" : "=v"(r) : "v"(lo), "v"(hi)); return r; }
;     __device__ __forceinline__ void operator()(const f32x4 (&acc)[2][2][4][2], const Unit& u, int wr, int wc, int fr, int fq, const float (&rsv)[8]) const {
;     ...
;                 for (int bj = 0; bj < 2; ++bj) { const size_t o_ = off + bj * HALF; f32x4 b0, b1;
;                     if (base_b) { const u32x4 w = __builtin_nontemporal_load((const u32x4*)(base_b + o_));
;                         b0 = (f32x4){__uint_as_float(w.x << 16), __uint_as_float(w.x & 0xffff0000u), __uint_as_float(w.y << 16), __uint_as_float(w.y & 0xffff0000u)};
;                         b1 = (f32x4){__uint_as_float(w.z << 16), __uint_as_float(w.z & 0xffff0000u), __uint_as_float(w.w << 16), __uint_as_float(w.w & 0xffff0000u)}; }
;                     else { b0 = __builtin_nontemporal_load((const f32x4*)(base_f + o_)); b1 = __builtin_nontemporal_load((const f32x4*)(base_f + o_ + 4)); }
;                     const f32x4 o0 = b0 + acc[ai][bj][m][0], o1 = b1 + acc[ai][bj][m][1];
;                     if (out_f) { *(f32x4*)(out_f + o_) = o0; *(f32x4*)(out_f + o_ + 4) = o1; }
;                     if (out_b) { u32x4 w; w.x = cvt_pk_bf16(o0[0], o0[1]); w.y = cvt_pk_bf16(o0[2], o0[3]); w.z = cvt_pk_bf16(o1[0], o1[1]); w.w = cvt_pk_bf16(o1[2], o1[3]); *(u32x4*)(out_b + o_) = w; }
.LBB0_1206:
	v_lshlrev_b64 v[122:123], 1, v[122:123]
	v_or_b32_e32 v122, 0x100, v122
	v_lshl_add_u64 v[122:123], s[74:75], 0, v[122:123]
	s_nop 1
	s_and_b64 vcc, exec, s[8:9]
	v_lshlrev_b32_e32 v126, 16, v188
	v_and_b32_e32 v127, 0xffff0000, v188
	v_lshlrev_b32_e32 v122, 16, v189
	v_and_b32_e32 v123, 0xffff0000, v189
	v_lshlrev_b32_e32 v128, 16, v190
	v_and_b32_e32 v129, 0xffff0000, v190
	v_lshlrev_b32_e32 v124, 16, v191
	v_and_b32_e32 v125, 0xffff0000, v191
	global_load_dwordx4 v[176:179], v[174:175], off nt
	global_load_dwordx4 v[180:183], v[174:175], off offset:256 nt
	v_lshl_add_u64 v[174:175], v[174:175], 0, s[40:41]
	global_load_dwordx4 v[184:187], v[174:175], off nt
	global_load_dwordx4 v[188:191], v[174:175], off offset:256 nt
	v_pk_add_f32 v[108:109], v[108:109], v[122:123]
	v_pk_add_f32 v[106:107], v[106:107], v[126:127]
	v_pk_add_f32 v[104:105], v[104:105], v[124:125]
	v_pk_add_f32 v[102:103], v[102:103], v[128:129]
	s_cbranch_vccnz .LBB0_1208
	global_store_dwordx4 v[120:121], v[106:109], off offset:512
	global_store_dwordx4 v[120:121], v[102:105], off offset:528

; __device__ __forceinline__ unsigned cvt_pk_bf16(float lo, float hi) { unsigned r; asm volatile("v_cvt_pk_bf16_f32 %0, %1, %2" : "=v"(r) : "v"(lo), "v"(hi)); return r; }
;     __device__ __forceinline__ void operator()(const f32x4 (&acc)[2][2][4][2], const Unit& u, int wr, int wc, int fr, int fq, const float (&rsv)[8]) const {
;     ...
;                 for (int bj = 0; bj < 2; ++bj) { const size_t o_ = off + bj * HALF; f32x4 b0, b1;
;                     if (base_b) { const u32x4 w = __builtin_nontemporal_load((const u32x4*)(base_b + o_));
;                         b0 = (f32x4){__uint_as_float(w.x << 16), __uint_as_float(w.x & 0xffff0000u), __uint_as_float(w.y << 16), __uint_as_float(w.y & 0xffff0000u)};
;                         b1 = (f32x4){__uint_as_float(w.z << 16), __uint_as_float(w.z & 0xffff0000u), __uint_as_float(w.w << 16), __uint_as_float(w.w & 0xffff0000u)}; }
;                     else { b0 = __builtin_nontemporal_load((const f32x4*)(base_f + o_)); b1 = __builtin_nontemporal_load((const f32x4*)(base_f + o_ + 4)); }
;                     const f32x4 o0 = b0 + acc[ai][bj][m][0], o1 = b1 + acc[ai][bj][m][1];
;                     if (out_f) { *(f32x4*)(out_f + o_) = o0; *(f32x4*)(out_f + o_ + 4) = o1; }
;                     if (out_b) { u32x4 w; w.x = cvt_pk_bf16(o0[0], o0[1]); w.y = cvt_pk_bf16(o0[2], o0[3]); w.z = cvt_pk_bf16(o1[0], o1[1]); w.w = cvt_pk_bf16(o1[2], o1[3]); *(u32x4*)(out_b + o_) = w; }
.LBB0_1216:
	v_or_b32_e32 v102, 32, v144
	s_waitcnt lgkmcnt(0)
	v_ashrrev_i32_e32 v103, 31, v102
	v_lshlrev_b64 v[102:103], 10, v[102:103]
	v_lshl_add_u64 v[106:107], v[102:103], 0, v[148:149]
	v_lshl_add_u64 v[102:103], v[106:107], 1, s[74:75]
	s_nop 1
	s_and_b64 vcc, exec, s[8:9]
	v_lshlrev_b32_e32 v108, 16, v192
	v_and_b32_e32 v109, 0xffff0000, v192
	v_lshlrev_b32_e32 v102, 16, v193
	v_and_b32_e32 v103, 0xffff0000, v193
	v_lshlrev_b32_e32 v110, 16, v194
	v_and_b32_e32 v111, 0xffff0000, v194
	v_lshlrev_b32_e32 v104, 16, v195
	v_and_b32_e32 v105, 0xffff0000, v195
	v_pk_add_f32 v[100:101], v[100:101], v[102:103]
	v_pk_add_f32 v[98:99], v[98:99], v[108:109]
	v_pk_add_f32 v[96:97], v[96:97], v[104:105]
	v_pk_add_f32 v[94:95], v[94:95], v[110:111]
	v_lshl_add_u64 v[104:105], v[106:107], 2, s[34:35]
	s_cbranch_vccnz .LBB0_1218
	global_store_dwordx4 v[104:105], v[98:101], off
	global_store_dwordx4 v[104:105], v[94:97], off offset:16

; __device__ __forceinline__ unsigned cvt_pk_bf16(float lo, float hi) { unsigned r; asm volatile("v_cvt_pk_bf16_f32 %0, %1, %2" : "=v"(r) : "v"(lo), "v"(hi)); return r; }
;     __device__ __forceinline__ void operator()(const f32x4 (&acc)[2][2][4][2], const Unit& u, int wr, int wc, int fr, int fq, const float (&rsv)[8]) const {
;     ...
;                 for (int bj = 0; bj < 2; ++bj) { const size_t o_ = off + bj * HALF; f32x4 b0, b1;
;                     if (base_b) { const u32x4 w = __builtin_nontemporal_load((const u32x4*)(base_b + o_));
;                         b0 = (f32x4){__uint_as_float(w.x << 16), __uint_as_float(w.x & 0xffff0000u), __uint_as_float(w.y << 16), __uint_as_float(w.y & 0xffff0000u)};
;                         b1 = (f32x4){__uint_as_float(w.z << 16), __uint_as_float(w.z & 0xffff0000u), __uint_as_float(w.w << 16), __uint_as_float(w.w & 0xffff0000u)}; }
;                     else { b0 = __builtin_nontemporal_load((const f32x4*)(base_f + o_)); b1 = __builtin_nontemporal_load((const f32x4*)(base_f + o_ + 4)); }
;                     const f32x4 o0 = b0 + acc[ai][bj][m][0], o1 = b1 + acc[ai][bj][m][1];
;                     if (out_f) { *(f32x4*)(out_f + o_) = o0; *(f32x4*)(out_f + o_ + 4) = o1; }
;                     if (out_b) { u32x4 w; w.x = cvt_pk_bf16(o0[0], o0[1]); w.y = cvt_pk_bf16(o0[2], o0[3]); w.z = cvt_pk_bf16(o1[0], o1[1]); w.w = cvt_pk_bf16(o1[2], o1[3]); *(u32x4*)(out_b + o_) = w; }
.LBB0_1222:
	v_lshlrev_b64 v[106:107], 1, v[106:107]
	v_or_b32_e32 v106, 0x100, v106
	v_lshl_add_u64 v[106:107], s[74:75], 0, v[106:107]
	s_nop 1
	s_and_b64 vcc, exec, s[8:9]
	v_lshlrev_b32_e32 v110, 16, v196
	v_and_b32_e32 v111, 0xffff0000, v196
	v_lshlrev_b32_e32 v106, 16, v197
	v_and_b32_e32 v107, 0xffff0000, v197
	v_lshlrev_b32_e32 v112, 16, v198
	v_and_b32_e32 v113, 0xffff0000, v198
	v_lshlrev_b32_e32 v108, 16, v199
	v_and_b32_e32 v109, 0xffff0000, v199
	v_pk_add_f32 v[92:93], v[92:93], v[106:107]
	v_pk_add_f32 v[90:91], v[90:91], v[110:111]
	v_pk_add_f32 v[88:89], v[88:89], v[108:109]
	v_pk_add_f32 v[86:87], v[86:87], v[112:113]
	s_cbranch_vccnz .LBB0_1224
	global_store_dwordx4 v[104:105], v[90:93], off offset:512
	global_store_dwordx4 v[104:105], v[86:89], off offset:528

; __device__ __forceinline__ unsigned cvt_pk_bf16(float lo, float hi) { unsigned r; asm volatile("v_cvt_pk_bf16_f32 %0, %1, %2" : "=v"(r) : "v"(lo), "v"(hi)); return r; }
;     __device__ __forceinline__ void operator()(const f32x4 (&acc)[2][2][4][2], const Unit& u, int wr, int wc, int fr, int fq, const float (&rsv)[8]) const {
;     ...
;                 for (int bj = 0; bj < 2; ++bj) { const size_t o_ = off + bj * HALF; f32x4 b0, b1;
;                     if (base_b) { const u32x4 w = __builtin_nontemporal_load((const u32x4*)(base_b + o_));
;                         b0 = (f32x4){__uint_as_float(w.x << 16), __uint_as_float(w.x & 0xffff0000u), __uint_as_float(w.y << 16), __uint_as_float(w.y & 0xffff0000u)};
;                         b1 = (f32x4){__uint_as_float(w.z << 16), __uint_as_float(w.z & 0xffff0000u), __uint_as_float(w.w << 16), __uint_as_float(w.w & 0xffff0000u)}; }
;                     else { b0 = __builtin_nontemporal_load((const f32x4*)(base_f + o_)); b1 = __builtin_nontemporal_load((const f32x4*)(base_f + o_ + 4)); }
;                     const f32x4 o0 = b0 + acc[ai][bj][m][0], o1 = b1 + acc[ai][bj][m][1];
;                     if (out_f) { *(f32x4*)(out_f + o_) = o0; *(f32x4*)(out_f + o_ + 4) = o1; }
;                     if (out_b) { u32x4 w; w.x = cvt_pk_bf16(o0[0], o0[1]); w.y = cvt_pk_bf16(o0[2], o0[3]); w.z = cvt_pk_bf16(o1[0], o1[1]); w.w = cvt_pk_bf16(o1[2], o1[3]); *(u32x4*)(out_b + o_) = w; }
.LBB0_1232:
	v_or_b32_e32 v86, 48, v144
	s_waitcnt lgkmcnt(0)
	v_ashrrev_i32_e32 v87, 31, v86
	v_lshlrev_b64 v[86:87], 10, v[86:87]
	v_lshl_add_u64 v[90:91], v[86:87], 0, v[148:149]
	v_lshl_add_u64 v[86:87], v[90:91], 1, s[74:75]
	s_nop 1
	s_and_b64 vcc, exec, s[8:9]
	v_lshlrev_b32_e32 v92, 16, v200
	v_and_b32_e32 v93, 0xffff0000, v200
	v_lshlrev_b32_e32 v86, 16, v201
	v_and_b32_e32 v87, 0xffff0000, v201
	v_lshlrev_b32_e32 v94, 16, v202
	v_and_b32_e32 v95, 0xffff0000, v202
	v_lshlrev_b32_e32 v88, 16, v203
	v_and_b32_e32 v89, 0xffff0000, v203
	v_pk_add_f32 v[84:85], v[84:85], v[86:87]
	v_pk_add_f32 v[82:83], v[82:83], v[92:93]
	v_pk_add_f32 v[80:81], v[80:81], v[88:89]
	v_pk_add_f32 v[78:79], v[78:79], v[94:95]
	v_lshl_add_u64 v[88:89], v[90:91], 2, s[34:35]
	s_cbranch_vccnz .LBB0_1234
	global_store_dwordx4 v[88:89], v[82:85], off
	global_store_dwordx4 v[88:89], v[78:81], off offset:16

; __device__ __forceinline__ unsigned cvt_pk_bf16(float lo, float hi) { unsigned r; asm volatile("v_cvt_pk_bf16_f32 %0, %1, %2" : "=v"(r) : "v"(lo), "v"(hi)); return r; }
;     __device__ __forceinline__ void operator()(const f32x4 (&acc)[2][2][4][2], const Unit& u, int wr, int wc, int fr, int fq, const float (&rsv)[8]) const {
;     ...
;                 for (int bj = 0; bj < 2; ++bj) { const size_t o_ = off + bj * HALF; f32x4 b0, b1;
;                     if (base_b) { const u32x4 w = __builtin_nontemporal_load((const u32x4*)(base_b + o_));
;                         b0 = (f32x4){__uint_as_float(w.x << 16), __uint_as_float(w.x & 0xffff0000u), __uint_as_float(w.y << 16), __uint_as_float(w.y & 0xffff0000u)};
;                         b1 = (f32x4){__uint_as_float(w.z << 16), __uint_as_float(w.z & 0xffff0000u), __uint_as_float(w.w << 16), __uint_as_float(w.w & 0xffff0000u)}; }
;                     else { b0 = __builtin_nontemporal_load((const f32x4*)(base_f + o_)); b1 = __builtin_nontemporal_load((const f32x4*)(base_f + o_ + 4)); }
;                     const f32x4 o0 = b0 + acc[ai][bj][m][0], o1 = b1 + acc[ai][bj][m][1];
;                     if (out_f) { *(f32x4*)(out_f + o_) = o0; *(f32x4*)(out_f + o_ + 4) = o1; }
;                     if (out_b) { u32x4 w; w.x = cvt_pk_bf16(o0[0], o0[1]); w.y = cvt_pk_bf16(o0[2], o0[3]); w.z = cvt_pk_bf16(o1[0], o1[1]); w.w = cvt_pk_bf16(o1[2], o1[3]); *(u32x4*)(out_b + o_) = w; }
.LBB0_1238:
	v_lshlrev_b64 v[90:91], 1, v[90:91]
	v_or_b32_e32 v90, 0x100, v90
	v_lshl_add_u64 v[90:91], s[74:75], 0, v[90:91]
	s_nop 1
	s_and_b64 vcc, exec, s[8:9]
	v_lshlrev_b32_e32 v94, 16, v204
	v_and_b32_e32 v95, 0xffff0000, v204
	v_lshlrev_b32_e32 v90, 16, v205
	v_and_b32_e32 v91, 0xffff0000, v205
	v_lshlrev_b32_e32 v96, 16, v206
	v_and_b32_e32 v97, 0xffff0000, v206
	v_lshlrev_b32_e32 v92, 16, v207
	v_and_b32_e32 v93, 0xffff0000, v207
	v_pk_add_f32 v[76:77], v[76:77], v[90:91]
	v_pk_add_f32 v[74:75], v[74:75], v[94:95]
	v_pk_add_f32 v[72:73], v[72:73], v[92:93]
	v_pk_add_f32 v[70:71], v[70:71], v[96:97]
	s_cbranch_vccnz .LBB0_1240
	global_store_dwordx4 v[88:89], v[74:77], off offset:512
	global_store_dwordx4 v[88:89], v[70:73], off offset:528

; __device__ __forceinline__ unsigned cvt_pk_bf16(float lo, float hi) { unsigned r; asm volatile("v_cvt_pk_bf16_f32 %0, %1, %2" : "=v"(r) : "v"(lo), "v"(hi)); return r; }
;     __device__ __forceinline__ void operator()(const f32x4 (&acc)[2][2][4][2], const Unit& u, int wr, int wc, int fr, int fq, const float (&rsv)[8]) const {
;     ...
;                 for (int bj = 0; bj < 2; ++bj) { const size_t o_ = off + bj * HALF; f32x4 b0, b1;
;                     if (base_b) { const u32x4 w = __builtin_nontemporal_load((const u32x4*)(base_b + o_));
;                         b0 = (f32x4){__uint_as_float(w.x << 16), __uint_as_float(w.x & 0xffff0000u), __uint_as_float(w.y << 16), __uint_as_float(w.y & 0xffff0000u)};
;                         b1 = (f32x4){__uint_as_float(w.z << 16), __uint_as_float(w.z & 0xffff0000u), __uint_as_float(w.w << 16), __uint_as_float(w.w & 0xffff0000u)}; }
;                     else { b0 = __builtin_nontemporal_load((const f32x4*)(base_f + o_)); b1 = __builtin_nontemporal_load((const f32x4*)(base_f + o_ + 4)); }
;                     const f32x4 o0 = b0 + acc[ai][bj][m][0], o1 = b1 + acc[ai][bj][m][1];
;                     if (out_f) { *(f32x4*)(out_f + o_) = o0; *(f32x4*)(out_f + o_ + 4) = o1; }
;                     if (out_b) { u32x4 w; w.x = cvt_pk_bf16(o0[0], o0[1]); w.y = cvt_pk_bf16(o0[2], o0[3]); w.z = cvt_pk_bf16(o1[0], o1[1]); w.w = cvt_pk_bf16(o1[2], o1[3]); *(u32x4*)(out_b + o_) = w; }
.LBB0_1248:
	s_mov_b64 s[38:39], 0x20000
	v_lshl_add_u64 v[74:75], v[146:147], 0, s[38:39]
	s_waitcnt lgkmcnt(0)
	v_lshl_add_u64 v[70:71], v[74:75], 1, s[74:75]
	s_nop 1
	s_and_b64 vcc, exec, s[8:9]
	v_lshlrev_b32_e32 v76, 16, v208
	v_and_b32_e32 v77, 0xffff0000, v208
	v_lshlrev_b32_e32 v70, 16, v209
	v_and_b32_e32 v71, 0xffff0000, v209
	v_lshlrev_b32_e32 v78, 16, v210
	v_and_b32_e32 v79, 0xffff0000, v210
	v_lshlrev_b32_e32 v72, 16, v211
	v_and_b32_e32 v73, 0xffff0000, v211
	v_pk_add_f32 v[68:69], v[68:69], v[70:71]
	v_pk_add_f32 v[66:67], v[66:67], v[76:77]
	v_pk_add_f32 v[64:65], v[64:65], v[72:73]
	v_pk_add_f32 v[62:63], v[62:63], v[78:79]
	v_lshl_add_u64 v[72:73], v[74:75], 2, s[34:35]
	s_cbranch_vccnz .LBB0_1250
	global_store_dwordx4 v[72:73], v[66:69], off
	global_store_dwordx4 v[72:73], v[62:65], off offset:16

; __device__ __forceinline__ unsigned cvt_pk_bf16(float lo, float hi) { unsigned r; asm volatile("v_cvt_pk_bf16_f32 %0, %1, %2" : "=v"(r) : "v"(lo), "v"(hi)); return r; }
;     __device__ __forceinline__ void operator()(const f32x4 (&acc)[2][2][4][2], const Unit& u, int wr, int wc, int fr, int fq, const float (&rsv)[8]) const {
;     ...
;                 for (int bj = 0; bj < 2; ++bj) { const size_t o_ = off + bj * HALF; f32x4 b0, b1;
;                     if (base_b) { const u32x4 w = __builtin_nontemporal_load((const u32x4*)(base_b + o_));
;                         b0 = (f32x4){__uint_as_float(w.x << 16), __uint_as_float(w.x & 0xffff0000u), __uint_as_float(w.y << 16), __uint_as_float(w.y & 0xffff0000u)};
;                         b1 = (f32x4){__uint_as_float(w.z << 16), __uint_as_float(w.z & 0xffff0000u), __uint_as_float(w.w << 16), __uint_as_float(w.w & 0xffff0000u)}; }
;                     else { b0 = __builtin_nontemporal_load((const f32x4*)(base_f + o_)); b1 = __builtin_nontemporal_load((const f32x4*)(base_f + o_ + 4)); }
;                     const f32x4 o0 = b0 + acc[ai][bj][m][0], o1 = b1 + acc[ai][bj][m][1];
;                     if (out_f) { *(f32x4*)(out_f + o_) = o0; *(f32x4*)(out_f + o_ + 4) = o1; }
;                     if (out_b) { u32x4 w; w.x = cvt_pk_bf16(o0[0], o0[1]); w.y = cvt_pk_bf16(o0[2], o0[3]); w.z = cvt_pk_bf16(o1[0], o1[1]); w.w = cvt_pk_bf16(o1[2], o1[3]); *(u32x4*)(out_b + o_) = w; }
.LBB0_1254:
	v_lshlrev_b64 v[74:75], 1, v[74:75]
	v_or_b32_e32 v74, 0x100, v74
	v_lshl_add_u64 v[74:75], s[74:75], 0, v[74:75]
	s_nop 1
	s_and_b64 vcc, exec, s[8:9]
	v_lshlrev_b32_e32 v78, 16, v212
	v_and_b32_e32 v79, 0xffff0000, v212
	v_lshlrev_b32_e32 v74, 16, v213
	v_and_b32_e32 v75, 0xffff0000, v213
	v_lshlrev_b32_e32 v80, 16, v214
	v_and_b32_e32 v81, 0xffff0000, v214
	v_lshlrev_b32_e32 v76, 16, v215
	v_and_b32_e32 v77, 0xffff0000, v215
	v_pk_add_f32 v[60:61], v[60:61], v[74:75]
	v_pk_add_f32 v[58:59], v[58:59], v[78:79]
	v_pk_add_f32 v[56:57], v[56:57], v[76:77]
	v_pk_add_f32 v[54:55], v[54:55], v[80:81]
	s_cbranch_vccnz .LBB0_1256
	global_store_dwordx4 v[72:73], v[58:61], off offset:512
	global_store_dwordx4 v[72:73], v[54:57], off offset:528

; __device__ __forceinline__ unsigned cvt_pk_bf16(float lo, float hi) { unsigned r; asm volatile("v_cvt_pk_bf16_f32 %0, %1, %2" : "=v"(r) : "v"(lo), "v"(hi)); return r; }
;     __device__ __forceinline__ void operator()(const f32x4 (&acc)[2][2][4][2], const Unit& u, int wr, int wc, int fr, int fq, const float (&rsv)[8]) const {
;     ...
;                 for (int bj = 0; bj < 2; ++bj) { const size_t o_ = off + bj * HALF; f32x4 b0, b1;
;                     if (base_b) { const u32x4 w = __builtin_nontemporal_load((const u32x4*)(base_b + o_));
;                         b0 = (f32x4){__uint_as_float(w.x << 16), __uint_as_float(w.x & 0xffff0000u), __uint_as_float(w.y << 16), __uint_as_float(w.y & 0xffff0000u)};
;                         b1 = (f32x4){__uint_as_float(w.z << 16), __uint_as_float(w.z & 0xffff0000u), __uint_as_float(w.w << 16), __uint_as_float(w.w & 0xffff0000u)}; }
;                     else { b0 = __builtin_nontemporal_load((const f32x4*)(base_f + o_)); b1 = __builtin_nontemporal_load((const f32x4*)(base_f + o_ + 4)); }
;                     const f32x4 o0 = b0 + acc[ai][bj][m][0], o1 = b1 + acc[ai][bj][m][1];
;                     if (out_f) { *(f32x4*)(out_f + o_) = o0; *(f32x4*)(out_f + o_ + 4) = o1; }
;                     if (out_b) { u32x4 w; w.x = cvt_pk_bf16(o0[0], o0[1]); w.y = cvt_pk_bf16(o0[2], o0[3]); w.z = cvt_pk_bf16(o1[0], o1[1]); w.w = cvt_pk_bf16(o1[2], o1[3]); *(u32x4*)(out_b + o_) = w; }
.LBB0_1264:
	s_mov_b64 s[38:39], 0x24000
	v_lshl_add_u64 v[58:59], v[146:147], 0, s[38:39]
	s_waitcnt lgkmcnt(0)
	v_lshl_add_u64 v[54:55], v[58:59], 1, s[74:75]
	s_nop 1
	s_and_b64 vcc, exec, s[8:9]
	v_lshlrev_b32_e32 v60, 16, v216
	v_and_b32_e32 v61, 0xffff0000, v216
	v_lshlrev_b32_e32 v54, 16, v217
	v_and_b32_e32 v55, 0xffff0000, v217
	v_lshlrev_b32_e32 v62, 16, v218
	v_and_b32_e32 v63, 0xffff0000, v218
	v_lshlrev_b32_e32 v56, 16, v219
	v_and_b32_e32 v57, 0xffff0000, v219
	v_pk_add_f32 v[52:53], v[52:53], v[54:55]
	v_pk_add_f32 v[50:51], v[50:51], v[60:61]
	v_pk_add_f32 v[48:49], v[48:49], v[56:57]
	v_pk_add_f32 v[46:47], v[46:47], v[62:63]
	v_lshl_add_u64 v[56:57], v[58:59], 2, s[34:35]
	s_cbranch_vccnz .LBB0_1266
	global_store_dwordx4 v[56:57], v[50:53], off
	global_store_dwordx4 v[56:57], v[46:49], off offset:16

; __device__ __forceinline__ unsigned cvt_pk_bf16(float lo, float hi) { unsigned r; asm volatile("v_cvt_pk_bf16_f32 %0, %1, %2" : "=v"(r) : "v"(lo), "v"(hi)); return r; }
;     __device__ __forceinline__ void operator()(const f32x4 (&acc)[2][2][4][2], const Unit& u, int wr, int wc, int fr, int fq, const float (&rsv)[8]) const {
;     ...
;                 for (int bj = 0; bj < 2; ++bj) { const size_t o_ = off + bj * HALF; f32x4 b0, b1;
;                     if (base_b) { const u32x4 w = __builtin_nontemporal_load((const u32x4*)(base_b + o_));
;                         b0 = (f32x4){__uint_as_float(w.x << 16), __uint_as_float(w.x & 0xffff0000u), __uint_as_float(w.y << 16), __uint_as_float(w.y & 0xffff0000u)};
;                         b1 = (f32x4){__uint_as_float(w.z << 16), __uint_as_float(w.z & 0xffff0000u), __uint_as_float(w.w << 16), __uint_as_float(w.w & 0xffff0000u)}; }
;                     else { b0 = __builtin_nontemporal_load((const f32x4*)(base_f + o_)); b1 = __builtin_nontemporal_load((const f32x4*)(base_f + o_ + 4)); }
;                     const f32x4 o0 = b0 + acc[ai][bj][m][0], o1 = b1 + acc[ai][bj][m][1];
;                     if (out_f) { *(f32x4*)(out_f + o_) = o0; *(f32x4*)(out_f + o_ + 4) = o1; }
;                     if (out_b) { u32x4 w; w.x = cvt_pk_bf16(o0[0], o0[1]); w.y = cvt_pk_bf16(o0[2], o0[3]); w.z = cvt_pk_bf16(o1[0], o1[1]); w.w = cvt_pk_bf16(o1[2], o1[3]); *(u32x4*)(out_b + o_) = w; }
.LBB0_1270:
	v_lshlrev_b64 v[58:59], 1, v[58:59]
	v_or_b32_e32 v58, 0x100, v58
	v_lshl_add_u64 v[58:59], s[74:75], 0, v[58:59]
	s_nop 1
	s_and_b64 vcc, exec, s[8:9]
	v_lshlrev_b32_e32 v62, 16, v220
	v_and_b32_e32 v63, 0xffff0000, v220
	v_lshlrev_b32_e32 v58, 16, v221
	v_and_b32_e32 v59, 0xffff0000, v221
	v_lshlrev_b32_e32 v64, 16, v222
	v_and_b32_e32 v65, 0xffff0000, v222
	v_lshlrev_b32_e32 v60, 16, v223
	v_and_b32_e32 v61, 0xffff0000, v223
	v_pk_add_f32 v[44:45], v[44:45], v[58:59]
	v_pk_add_f32 v[42:43], v[42:43], v[62:63]
	v_pk_add_f32 v[40:41], v[40:41], v[60:61]
	v_pk_add_f32 v[38:39], v[38:39], v[64:65]
	s_cbranch_vccnz .LBB0_1272
	global_store_dwordx4 v[56:57], v[42:45], off offset:512
	global_store_dwordx4 v[56:57], v[38:41], off offset:528

; __device__ __forceinline__ unsigned cvt_pk_bf16(float lo, float hi) { unsigned r; asm volatile("v_cvt_pk_bf16_f32 %0, %1, %2" : "=v"(r) : "v"(lo), "v"(hi)); return r; }
;     __device__ __forceinline__ void operator()(const f32x4 (&acc)[2][2][4][2], const Unit& u, int wr, int wc, int fr, int fq, const float (&rsv)[8]) const {
;     ...
;                 for (int bj = 0; bj < 2; ++bj) { const size_t o_ = off + bj * HALF; f32x4 b0, b1;
;                     if (base_b) { const u32x4 w = __builtin_nontemporal_load((const u32x4*)(base_b + o_));
;                         b0 = (f32x4){__uint_as_float(w.x << 16), __uint_as_float(w.x & 0xffff0000u), __uint_as_float(w.y << 16), __uint_as_float(w.y & 0xffff0000u)};
;                         b1 = (f32x4){__uint_as_float(w.z << 16), __uint_as_float(w.z & 0xffff0000u), __uint_as_float(w.w << 16), __uint_as_float(w.w & 0xffff0000u)}; }
;                     else { b0 = __builtin_nontemporal_load((const f32x4*)(base_f + o_)); b1 = __builtin_nontemporal_load((const f32x4*)(base_f + o_ + 4)); }
;                     const f32x4 o0 = b0 + acc[ai][bj][m][0], o1 = b1 + acc[ai][bj][m][1];
;                     if (out_f) { *(f32x4*)(out_f + o_) = o0; *(f32x4*)(out_f + o_ + 4) = o1; }
;                     if (out_b) { u32x4 w; w.x = cvt_pk_bf16(o0[0], o0[1]); w.y = cvt_pk_bf16(o0[2], o0[3]); w.z = cvt_pk_bf16(o1[0], o1[1]); w.w = cvt_pk_bf16(o1[2], o1[3]); *(u32x4*)(out_b + o_) = w; }
.LBB0_1280:
	s_mov_b64 s[38:39], 0x28000
	v_lshl_add_u64 v[42:43], v[146:147], 0, s[38:39]
	s_waitcnt lgkmcnt(0)
	v_lshl_add_u64 v[38:39], v[42:43], 1, s[74:75]
	s_nop 1
	s_and_b64 vcc, exec, s[8:9]
	s_waitcnt vmcnt(0)
	v_lshlrev_b32_e32 v44, 16, v176
	v_and_b32_e32 v45, 0xffff0000, v176
	v_lshlrev_b32_e32 v38, 16, v177
	v_and_b32_e32 v39, 0xffff0000, v177
	v_lshlrev_b32_e32 v46, 16, v178
	v_and_b32_e32 v47, 0xffff0000, v178
	v_lshlrev_b32_e32 v40, 16, v179
	v_and_b32_e32 v41, 0xffff0000, v179
	v_pk_add_f32 v[36:37], v[36:37], v[38:39]
	v_pk_add_f32 v[34:35], v[34:35], v[44:45]
	v_pk_add_f32 v[32:33], v[32:33], v[40:41]
	v_pk_add_f32 v[30:31], v[30:31], v[46:47]
	v_lshl_add_u64 v[40:41], v[42:43], 2, s[34:35]
	s_cbranch_vccnz .LBB0_1282
	global_store_dwordx4 v[40:41], v[34:37], off
	global_store_dwordx4 v[40:41], v[30:33], off offset:16

; __device__ __forceinline__ unsigned cvt_pk_bf16(float lo, float hi) { unsigned r; asm volatile("v_cvt_pk_bf16_f32 %0, %1, %2" : "=v"(r) : "v"(lo), "v"(hi)); return r; }
;     __device__ __forceinline__ void operator()(const f32x4 (&acc)[2][2][4][2], const Unit& u, int wr, int wc, int fr, int fq, const float (&rsv)[8]) const {
;     ...
;                 for (int bj = 0; bj < 2; ++bj) { const size_t o_ = off + bj * HALF; f32x4 b0, b1;
;                     if (base_b) { const u32x4 w = __builtin_nontemporal_load((const u32x4*)(base_b + o_));
;                         b0 = (f32x4){__uint_as_float(w.x << 16), __uint_as_float(w.x & 0xffff0000u), __uint_as_float(w.y << 16), __uint_as_float(w.y & 0xffff0000u)};
;                         b1 = (f32x4){__uint_as_float(w.z << 16), __uint_as_float(w.z & 0xffff0000u), __uint_as_float(w.w << 16), __uint_as_float(w.w & 0xffff0000u)}; }
;                     else { b0 = __builtin_nontemporal_load((const f32x4*)(base_f + o_)); b1 = __builtin_nontemporal_load((const f32x4*)(base_f + o_ + 4)); }
;                     const f32x4 o0 = b0 + acc[ai][bj][m][0], o1 = b1 + acc[ai][bj][m][1];
;                     if (out_f) { *(f32x4*)(out_f + o_) = o0; *(f32x4*)(out_f + o_ + 4) = o1; }
;                     if (out_b) { u32x4 w; w.x = cvt_pk_bf16(o0[0], o0[1]); w.y = cvt_pk_bf16(o0[2], o0[3]); w.z = cvt_pk_bf16(o1[0], o1[1]); w.w = cvt_pk_bf16(o1[2], o1[3]); *(u32x4*)(out_b + o_) = w; }
.LBB0_1286:
	v_lshlrev_b64 v[42:43], 1, v[42:43]
	v_or_b32_e32 v42, 0x100, v42
	v_lshl_add_u64 v[42:43], s[74:75], 0, v[42:43]
	s_nop 1
	s_and_b64 vcc, exec, s[8:9]
	v_lshlrev_b32_e32 v46, 16, v180
	v_and_b32_e32 v47, 0xffff0000, v180
	v_lshlrev_b32_e32 v42, 16, v181
	v_and_b32_e32 v43, 0xffff0000, v181
	v_lshlrev_b32_e32 v48, 16, v182
	v_and_b32_e32 v49, 0xffff0000, v182
	v_lshlrev_b32_e32 v44, 16, v183
	v_and_b32_e32 v45, 0xffff0000, v183
	v_pk_add_f32 v[28:29], v[28:29], v[42:43]
	v_pk_add_f32 v[26:27], v[26:27], v[46:47]
	v_pk_add_f32 v[24:25], v[24:25], v[44:45]
	v_pk_add_f32 v[22:23], v[22:23], v[48:49]
	s_cbranch_vccnz .LBB0_1288
	global_store_dwordx4 v[40:41], v[26:29], off offset:512
	global_store_dwordx4 v[40:41], v[22:25], off offset:528

; __device__ __forceinline__ unsigned cvt_pk_bf16(float lo, float hi) { unsigned r; asm volatile("v_cvt_pk_bf16_f32 %0, %1, %2" : "=v"(r) : "v"(lo), "v"(hi)); return r; }
;     __device__ __forceinline__ void operator()(const f32x4 (&acc)[2][2][4][2], const Unit& u, int wr, int wc, int fr, int fq, const float (&rsv)[8]) const {
;     ...
;                 for (int bj = 0; bj < 2; ++bj) { const size_t o_ = off + bj * HALF; f32x4 b0, b1;
;                     if (base_b) { const u32x4 w = __builtin_nontemporal_load((const u32x4*)(base_b + o_));
;                         b0 = (f32x4){__uint_as_float(w.x << 16), __uint_as_float(w.x & 0xffff0000u), __uint_as_float(w.y << 16), __uint_as_float(w.y & 0xffff0000u)};
;                         b1 = (f32x4){__uint_as_float(w.z << 16), __uint_as_float(w.z & 0xffff0000u), __uint_as_float(w.w << 16), __uint_as_float(w.w & 0xffff0000u)}; }
;                     else { b0 = __builtin_nontemporal_load((const f32x4*)(base_f + o_)); b1 = __builtin_nontemporal_load((const f32x4*)(base_f + o_ + 4)); }
;                     const f32x4 o0 = b0 + acc[ai][bj][m][0], o1 = b1 + acc[ai][bj][m][1];
;                     if (out_f) { *(f32x4*)(out_f + o_) = o0; *(f32x4*)(out_f + o_ + 4) = o1; }
;                     if (out_b) { u32x4 w; w.x = cvt_pk_bf16(o0[0], o0[1]); w.y = cvt_pk_bf16(o0[2], o0[3]); w.z = cvt_pk_bf16(o1[0], o1[1]); w.w = cvt_pk_bf16(o1[2], o1[3]); *(u32x4*)(out_b + o_) = w; }
.LBB0_1296:
	s_mov_b64 s[38:39], 0x2c000
	v_lshl_add_u64 v[26:27], v[146:147], 0, s[38:39]
	s_waitcnt lgkmcnt(0)
	v_lshl_add_u64 v[22:23], v[26:27], 1, s[74:75]
	s_nop 1
	s_and_b64 vcc, exec, s[8:9]
	v_lshlrev_b32_e32 v28, 16, v184
	v_and_b32_e32 v29, 0xffff0000, v184
	v_lshlrev_b32_e32 v22, 16, v185
	v_and_b32_e32 v23, 0xffff0000, v185
	v_lshlrev_b32_e32 v30, 16, v186
	v_and_b32_e32 v31, 0xffff0000, v186
	v_lshlrev_b32_e32 v24, 16, v187
	v_and_b32_e32 v25, 0xffff0000, v187
	v_pk_add_f32 v[20:21], v[20:21], v[22:23]
	v_pk_add_f32 v[18:19], v[18:19], v[28:29]
	v_pk_add_f32 v[16:17], v[16:17], v[24:25]
	v_pk_add_f32 v[14:15], v[14:15], v[30:31]
	v_lshl_add_u64 v[24:25], v[26:27], 2, s[34:35]
	s_cbranch_vccnz .LBB0_1298
	global_store_dwordx4 v[24:25], v[18:21], off
	global_store_dwordx4 v[24:25], v[14:17], off offset:16

; __device__ __forceinline__ unsigned cvt_pk_bf16(float lo, float hi) { unsigned r; asm volatile("v_cvt_pk_bf16_f32 %0, %1, %2" : "=v"(r) : "v"(lo), "v"(hi)); return r; }
;     __device__ __forceinline__ void operator()(const f32x4 (&acc)[2][2][4][2], const Unit& u, int wr, int wc, int fr, int fq, const float (&rsv)[8]) const {
;     ...
;                 for (int bj = 0; bj < 2; ++bj) { const size_t o_ = off + bj * HALF; f32x4 b0, b1;
;                     if (base_b) { const u32x4 w = __builtin_nontemporal_load((const u32x4*)(base_b + o_));
;                         b0 = (f32x4){__uint_as_float(w.x << 16), __uint_as_float(w.x & 0xffff0000u), __uint_as_float(w.y << 16), __uint_as_float(w.y & 0xffff0000u)};
;                         b1 = (f32x4){__uint_as_float(w.z << 16), __uint_as_float(w.z & 0xffff0000u), __uint_as_float(w.w << 16), __uint_as_float(w.w & 0xffff0000u)}; }
;                     else { b0 = __builtin_nontemporal_load((const f32x4*)(base_f + o_)); b1 = __builtin_nontemporal_load((const f32x4*)(base_f + o_ + 4)); }
;                     const f32x4 o0 = b0 + acc[ai][bj][m][0], o1 = b1 + acc[ai][bj][m][1];
;                     if (out_f) { *(f32x4*)(out_f + o_) = o0; *(f32x4*)(out_f + o_ + 4) = o1; }
;                     if (out_b) { u32x4 w; w.x = cvt_pk_bf16(o0[0], o0[1]); w.y = cvt_pk_bf16(o0[2], o0[3]); w.z = cvt_pk_bf16(o1[0], o1[1]); w.w = cvt_pk_bf16(o1[2], o1[3]); *(u32x4*)(out_b + o_) = w; }
.LBB0_1302:
	v_lshlrev_b64 v[26:27], 1, v[26:27]
	v_or_b32_e32 v26, 0x100, v26
	v_lshl_add_u64 v[26:27], s[74:75], 0, v[26:27]
	s_nop 1
	s_and_b64 vcc, exec, s[8:9]
	v_lshlrev_b32_e32 v30, 16, v188
	v_and_b32_e32 v31, 0xffff0000, v188
	v_lshlrev_b32_e32 v26, 16, v189
	v_and_b32_e32 v27, 0xffff0000, v189
	v_lshlrev_b32_e32 v32, 16, v190
	v_and_b32_e32 v33, 0xffff0000, v190
	v_lshlrev_b32_e32 v28, 16, v191
	v_and_b32_e32 v29, 0xffff0000, v191
	v_pk_add_f32 v[12:13], v[12:13], v[26:27]
	v_pk_add_f32 v[10:11], v[10:11], v[30:31]
	v_pk_add_f32 v[8:9], v[8:9], v[28:29]
	v_pk_add_f32 v[6:7], v[6:7], v[32:33]
	s_cbranch_vccnz .LBB0_1304
	global_store_dwordx4 v[24:25], v[10:13], off offset:512
	global_store_dwordx4 v[24:25], v[6:9], off offset:528
